# attention loops: ring-slot address block moved from after the loop-back barrier to before it (loop-edge rotation), bit-identical
# speedup vs baseline: 1.0005x; 1.0005x over previous
; DEV int ltid() { int t = threadIdx.x; asm volatile("" : "+v"(t)); return t; }
; DEV int v_st(int k, int c) { const int kk = (k & ~0xC) | ((k & 4) << 1) | ((k & 8) >> 1); return ((kk >> 3) * 4 + (c >> 5)) * 512 + ((kk & 7) * 32 + (c & 31)) * 2; }
; DEV int v_rd_base(int lane) { return ((lane & 3) << 3) | (((lane >> 2) & 3) << 6) | (((lane >> 4) & 1) << 5) | (((lane >> 5) & 1) << 8); }
; #define SLOAD(i, k0) do { sr_[i].vs0 = *reinterpret_cast<const bf16x8*>(&Vh[(size_t)((k0) + sr) * 128 + sc]); sr_[i].vs1 = *reinterpret_cast<const bf16x8*>(&Vh[(size_t)((k0) + 32 + sr) * 128 + sc]); \
;     sr_[i].ks0 = *reinterpret_cast<const bf16x8*>(&Kh[(size_t)((k0) + kr) * 64 + kc]); } while (0)
; #define SWRITE(b, i) do { *(bf16x8*)(V_lds + (b) * AT_SHM_V + vst0) = sr_[i].vs0; *(bf16x8*)(V_lds + (b) * AT_SHM_V + vst1) = sr_[i].vs1; \
;     *(bf16x8*)(K_lds + (b) * AT_SHM_K + kst) = sr_[i].ks0; } while (0)
; DEV void attn_pass(const u16* __restrict__ Qb, const u16* __restrict__ Kh, const u16* __restrict__ Vh, int seq, f32x16* o, float* rli) {
;     ...
;   const int tid = ltid(), wid = tid >> 6, lane = tid & 63, r32 = lane & 31, hi = lane >> 5;
;   char* V_lds = lds; char* K_lds = lds + 3 * AT_SHM_V;
;   float* wsx = (float*)(lds + 3 * AT_SHM_V + 3 * AT_SHM_K) + wid * 64; float* li_l = wsx; float* al_l = wsx + 32;
;   float m_reg = -1e30f, l_reg = 0; bf16x8 qr[4];
; #pragma unroll
;   for (int d = 0; d < 4; ++d) o[d] = f32x16{};
;   const u16* Qw = Qb + (size_t)(wid * 32 + r32) * 64 + hi * 8;
; #pragma unroll
;   for (int d0 = 0; d0 < 4; ++d0) qr[d0] = *reinterpret_cast<const bf16x8*>(Qw + d0 * 16);
;   const int sr = tid >> 4, sc = (tid & 15) * 8, vst0 = v_st(sr, sc), vst1 = v_st(32 + sr, sc);
;   const int kr = tid >> 3, kc = (tid & 7) * 8, kst = KSWZ64(kr, kc * 2);
;   const int vb0 = (int)(uintptr_t)(__attribute__((address_space(3))) char*)V_lds + v_rd_base(lane);
;   struct { bf16x8 vs0, vs1, ks0; } sr_[2];
;     ...
;   f32x16 pA0, pA1, pB0, pB1; float mnA, mnB, alA, alB; bf16x8 pa0, pa1, pa2, pa3; const int NT = seq / 64;
;   constexpr int SE = 0, SO = 1;
;   SLOAD(SE, 0); SLOAD(SO, 64);
;   asm volatile("s_waitcnt vmcnt(3)" ::: "memory"); SWRITE(0, SE); __syncthreads();
;   if (2 < NT) SLOAD(SE, 2 * 64);
;   qkt(pA0, pA1, K_lds, qr, r32, hi); partialSM(pA0, pA1, m_reg, mnA, alA);
.LBB0_69:
	s_and_b32 s43, s10, 7
	s_addk_i32 s11, 0x100
	s_and_b64 s[6:7], s[6:7], exec
	s_cselect_b32 s44, 4, 0x44
	s_cselect_b32 s46, 0, s11
	s_lshl_b32 s1, s0, 3
	s_or_b32 s49, s1, s43
	s_mul_i32 s52, s49, 0x110000
	s_mul_hi_i32 s53, s49, 0x110000
	s_add_u32 s64, s40, s52
	s_addc_u32 s65, s41, s53
	s_lshl_b32 s0, s0, 4
	s_lshl_b32 s1, s43, 1
	s_or_b32 s47, s0, s1
	s_mul_i32 s0, s47, 0x1100
	s_mul_hi_i32 s1, s47, 0x1100
	s_add_u32 s0, s0, s46
	v_mov_b32_e32 v70, v252
	s_addc_u32 s1, s1, 0
	s_lshl_b64 s[0:1], s[0:1], 7
	v_ashrrev_i32_e32 v48, 4, v70
	v_lshlrev_b32_e32 v20, 3, v70
	v_ashrrev_i32_e32 v49, 31, v48
	s_add_u32 s0, s36, s0
	v_and_b32_e32 v2, 0x78, v20
	v_add_u32_e32 v12, 32, v48
	v_lshlrev_b64 v[50:51], 8, v[48:49]
	s_addc_u32 s1, s37, s1
	s_mul_i32 s62, s47, 0x88000
	v_ashrrev_i32_e32 v14, 3, v70
	v_lshl_add_u64 v[0:1], s[64:65], 0, v[50:51]
	v_lshlrev_b32_e32 v2, 1, v2
	v_mov_b32_e32 v3, v163
	v_ashrrev_i32_e32 v13, 31, v12
	s_mul_hi_i32 s63, s47, 0x88000
	s_add_u32 s6, s38, s62
	v_lshl_add_u64 v[66:67], v[0:1], 0, v[2:3]
	v_lshlrev_b64 v[0:1], 8, v[12:13]
	v_ashrrev_i32_e32 v15, 31, v14
	s_addc_u32 s7, s39, s63
	v_lshlrev_b32_e32 v71, 4, v70
	v_lshl_add_u64 v[0:1], s[64:65], 0, v[0:1]
	v_lshlrev_b64 v[52:53], 7, v[14:15]
	v_and_b32_e32 v16, 0x70, v71
	v_lshl_add_u64 v[4:5], v[0:1], 0, v[2:3]
	v_lshl_add_u64 v[8:9], s[6:7], 0, v[52:53]
	v_mov_b32_e32 v17, v163
	global_load_dwordx4 v[0:3], v[66:67], off
	s_nop 0
	global_load_dwordx4 v[4:7], v[4:5], off
	v_lshl_add_u64 v[68:69], v[8:9], 0, v[16:17]
	global_load_dwordx4 v[8:11], v[68:69], off
	v_ashrrev_i32_e32 v13, 1, v70
	v_bfi_b32 v18, s68, v13, v70
	v_ashrrev_i32_e32 v19, 31, v18
	v_lshlrev_b64 v[18:19], 7, v[18:19]
	v_lshrrev_b32_e32 v13, 1, v70
	v_lshl_add_u64 v[18:19], s[0:1], 0, v[18:19]
	v_and_b32_e32 v162, 16, v13
	v_lshl_add_u64 v[18:19], v[18:19], 0, v[162:163]
	global_load_dwordx4 v[108:111], v[18:19], off
	global_load_dwordx4 v[104:107], v[18:19], off offset:32
	global_load_dwordx4 v[100:103], v[18:19], off offset:64
	global_load_dwordx4 v[96:99], v[18:19], off offset:96
	v_and_b32_e32 v13, 0xfffff0, v48
	v_lshlrev_b32_e32 v15, 1, v48
	v_and_or_b32 v13, v15, 8, v13
	v_lshrrev_b32_e32 v13, 1, v13
	v_bfe_u32 v17, v20, 5, 2
	v_lshrrev_b32_e32 v15, 1, v48
	v_or_b32_e32 v13, v13, v17
	v_and_b32_e32 v73, 3, v48
	v_lshlrev_b32_e32 v72, 9, v13
	v_and_or_b32 v13, v15, 4, v73
	v_and_b32_e32 v15, 0xfffff0, v12
	v_lshlrev_b32_e32 v12, 1, v12
	v_and_or_b32 v12, v12, 8, v15
	v_lshrrev_b32_e32 v12, 1, v12
	v_or_b32_e32 v12, v12, v17
	v_lshlrev_b32_e32 v13, 6, v13
	v_and_b32_e32 v74, 48, v71
	v_lshlrev_b32_e32 v75, 9, v12
	v_or3_b32 v18, v72, v13, v74
	v_or3_b32 v17, v75, v13, v74
	v_lshlrev_b32_e32 v12, 7, v14
	v_and_b32_e32 v13, 0x70, v70
	v_bitop3_b32 v76, v16, v12, v13 bitop3:0xde
	v_add_co_u32_e32 v12, vcc, s75, v66
	s_movk_i32 s0, 0x6000
	s_nop 0
	v_addc_co_u32_e32 v13, vcc, 0, v67, vcc
	global_load_dwordx4 v[54:57], v[12:13], off
	v_add_co_u32_e32 v12, vcc, s0, v66
	v_and_b32_e32 v49, 31, v70
	s_nop 0
	v_addc_co_u32_e32 v13, vcc, 0, v67, vcc
	v_add_co_u32_e32 v14, vcc, s45, v68
	v_lshlrev_b32_e32 v80, 7, v49
	s_nop 0
	v_addc_co_u32_e32 v15, vcc, 0, v69, vcc
	global_load_dwordx4 v[58:61], v[12:13], off
	global_load_dwordx4 v[62:65], v[14:15], off
	v_and_b32_e32 v81, 0x70, v20
	v_add_u32_e32 v77, 0, v18
	v_add_u32_e32 v78, 0, v17
	v_bitop3_b32 v171, v162, v80, v81 bitop3:0xde
	s_waitcnt vmcnt(3)
	v_add_u32_e32 v79, 0, v76
	v_or_b32_e32 v83, 32, v162
	s_add_i32 s48, 0, 0x12000
	v_bitop3_b32 v175, v83, v80, v81 bitop3:0xde
	v_and_b32_e32 v82, 63, v70
	s_mov_b32 s0, 0xa000
	v_and_b32_e32 v177, 0xc0, v71
	v_or_b32_e32 v71, 64, v162
	v_bitop3_b32 v174, v71, v80, v81 bitop3:0xde
	v_or_b32_e32 v84, 0x60, v162
	v_bitop3_b32 v173, v84, v80, v81 bitop3:0xde
	s_mov_b32 s8, 0
	s_mov_b32 s9, s8
	s_mov_b32 s10, s8
	s_mov_b32 s11, s8
	s_mov_b32 s12, s8
	s_mov_b32 s13, s8
	s_mov_b32 s14, s8
	s_mov_b32 s15, s8
	s_mov_b32 s16, s8
	s_mov_b32 s17, s8
	s_waitcnt vmcnt(9)
	ds_write_b128 v77, v[0:3]
	s_waitcnt vmcnt(8)
	ds_write_b128 v78, v[4:7]
	v_add_u32_e32 v4, 0, v171
	s_waitcnt vmcnt(7)
	ds_write_b128 v79, v[8:11] offset:49152
	s_waitcnt lgkmcnt(0)
	s_barrier
	ds_read_b128 v[0:3], v4 offset:49152
	ds_read_b128 v[4:7], v4 offset:53248
	v_and_b32_e32 v8, 0x3fffffc0, v70
	v_lshl_add_u32 v168, v8, 2, s48
	v_add_u32_e32 v8, 0, v175
	s_waitcnt vmcnt(6) lgkmcnt(1)
	v_mfma_f32_32x32x16_bf16 v[16:31], v[0:3], v[108:111], 0
	ds_read_b128 v[0:3], v8 offset:49152
	s_mov_b32 s18, s8
	s_mov_b32 s19, s8
	s_mov_b32 s20, s8
	s_mov_b32 s21, s8
	s_mov_b32 s22, s8
	s_mov_b32 s23, s8
	s_waitcnt lgkmcnt(1)
	v_mfma_f32_32x32x16_bf16 v[32:47], v[4:7], v[108:111], 0
	v_lshlrev_b32_e32 v4, 3, v82
	v_lshlrev_b32_e32 v5, 1, v70
	v_and_b32_e32 v176, 24, v4
	v_and_b32_e32 v178, 32, v5
	v_and_b32_e32 v179, 0x100, v4
	ds_read_b128 v[4:7], v8 offset:53248
	v_add_co_u32_e32 v8, vcc, s75, v68
	s_waitcnt vmcnt(5) lgkmcnt(0)
	v_mfma_f32_32x32x16_bf16 v[32:47], v[4:7], v[104:107], v[32:47]
	v_addc_co_u32_e32 v9, vcc, 0, v69, vcc
	v_add_co_u32_e32 v10, vcc, s0, v66
	s_mov_b32 s0, 0x8000
	s_nop 0
	v_addc_co_u32_e32 v11, vcc, 0, v67, vcc
	v_add_co_u32_e32 v4, vcc, s0, v66
	v_add_u32_e32 v6, 0, v174
	s_nop 0
	v_addc_co_u32_e32 v5, vcc, 0, v67, vcc
	v_mfma_f32_32x32x16_bf16 v[16:31], v[0:3], v[104:107], v[16:31]
	ds_read_b128 v[0:3], v6 offset:49152
	global_load_dwordx4 v[120:123], v[8:9], off
	global_load_dwordx4 v[112:115], v[10:11], off
	global_load_dwordx4 v[116:119], v[4:5], off
	v_add_u32_e32 v8, 0, v173
	ds_read_b128 v[4:7], v6 offset:53248
	ds_read_b128 v[66:69], v8 offset:53248
	s_mov_b32 s0, 0x10000
	s_waitcnt vmcnt(7) lgkmcnt(2)
; #define SLOAD(i, k0) do { sr_[i].vs0 = *reinterpret_cast<const bf16x8*>(&Vh[(size_t)((k0) + sr) * 128 + sc]); sr_[i].vs1 = *reinterpret_cast<const bf16x8*>(&Vh[(size_t)((k0) + 32 + sr) * 128 + sc]); \
;     sr_[i].ks0 = *reinterpret_cast<const bf16x8*>(&Kh[(size_t)((k0) + kr) * 64 + kc]); } while (0)
; #define SWRITE(b, i) do { *(bf16x8*)(V_lds + (b) * AT_SHM_V + vst0) = sr_[i].vs0; *(bf16x8*)(V_lds + (b) * AT_SHM_V + vst1) = sr_[i].vs1; \
;     *(bf16x8*)(K_lds + (b) * AT_SHM_K + kst) = sr_[i].ks0; } while (0)
; #define SWAIT() asm volatile("s_waitcnt vmcnt(3)" ::: "memory")
; DEV void partialSM(f32x16& p0, f32x16& p1, float& m_reg, float& mn, float& alpha) {
;   constexpr float C = AT_SCALE * 1.4426950408889634f;
;   float pmax = p0[0];
; #pragma unroll
;   for (int r = 1; r < 16; ++r) pmax = fmaxf(pmax, p0[r]);
; #pragma unroll
;   for (int r = 0; r < 16; ++r) pmax = fmaxf(pmax, p1[r]);
;   { auto rr = __builtin_amdgcn_permlane32_swap(__float_as_uint(pmax), __float_as_uint(pmax), false, false);
;     pmax = fmaxf(__uint_as_float(rr[0]), __uint_as_float(rr[1])); }
;   if (__builtin_expect(__all(pmax - m_reg <= AT_THR / AT_SCALE), 1)) { mn = m_reg; alpha = 1.f; }
;   else { mn = fmaxf(m_reg, pmax); alpha = __builtin_amdgcn_exp2f((m_reg - mn) * C); m_reg = mn; }
;   float mnC = -mn * C;
; #pragma unroll
;   for (int r = 0; r < 16; ++r) p0[r] = fmaf(p0[r], C, mnC);
; #pragma unroll
;   for (int r = 0; r < 16; ++r) p1[r] = fmaf(p1[r], C, mnC);
; #pragma unroll
;   for (int r = 0; r < 16; ++r) p0[r] = __builtin_amdgcn_exp2f(p0[r]);
; }
; DEV void attn_pass(const u16* __restrict__ Qb, const u16* __restrict__ Kh, const u16* __restrict__ Vh, int seq, f32x16* o, float* rli) {
;     ...
;   SLOAD(SE, 0); SLOAD(SO, 64);
;   asm volatile("s_waitcnt vmcnt(3)" ::: "memory"); SWRITE(0, SE); __syncthreads();
;   if (2 < NT) SLOAD(SE, 2 * 64);
;   qkt(pA0, pA1, K_lds, qr, r32, hi); partialSM(pA0, pA1, m_reg, mnA, alA);
;   SWAIT(); SWRITE(1, SO); __syncthreads();
; #pragma unroll 1
;   for (int j = 1; j + 1 < NT; j += 2) {
;     const int bm1 = (j - 1) % 3, b0 = j % 3, b1 = (j + 1) % 3, b2 = (j + 2) % 3;
	v_mfma_f32_32x32x16_bf16 v[16:31], v[0:3], v[100:103], v[16:31]
	ds_read_b128 v[0:3], v8 offset:49152
	s_waitcnt vmcnt(3)
	s_waitcnt vmcnt(5)
	ds_write_b128 v77, v[54:57] offset:16384
	s_waitcnt vmcnt(4)
	ds_write_b128 v78, v[58:61] offset:16384
	s_waitcnt vmcnt(3)
	ds_write_b128 v79, v[62:65] offset:57344
	v_mov_b32_e32 v54, 0xf149f2ca
	v_bitop3_b32 v183, v162, s0, v81 bitop3:0xde
	v_bitop3_b32 v185, v83, s0, v81 bitop3:0xde
	v_bitop3_b32 v199, v71, s0, v81 bitop3:0xde
	s_waitcnt lgkmcnt(5)
	v_mfma_f32_32x32x16_bf16 v[32:47], v[4:7], v[100:103], v[32:47]
	v_bitop3_b32 v201, v84, s0, v81 bitop3:0xde
	v_lshl_add_u32 v169, v49, 2, v168
	s_mov_b32 s45, 4
	s_mov_b32 s50, 3
	s_mov_b32 s51, 1
	s_mov_b32 s66, 2
	v_cmp_gt_u32_e64 s[6:7], 32, v82
	s_waitcnt lgkmcnt(3)
	v_mfma_f32_32x32x16_bf16 v[16:31], v[0:3], v[96:99], v[16:31]
	v_mov_b64_e32 v[0:1], s[8:9]
	v_mov_b64_e32 v[2:3], s[10:11]
	v_mov_b64_e32 v[4:5], s[12:13]
	v_mov_b64_e32 v[6:7], s[14:15]
	v_mov_b64_e32 v[8:9], s[16:17]
	v_mov_b64_e32 v[10:11], s[18:19]
	v_mov_b64_e32 v[12:13], s[20:21]
	v_mfma_f32_32x32x16_bf16 v[32:47], v[66:69], v[96:99], v[32:47]
	s_nop 3
	v_max_f32_e32 v66, v17, v17
	v_max_f32_e32 v67, v16, v16
	v_max_f32_e32 v66, v67, v66
	v_max3_f32 v66, v66, v18, v19
	v_max3_f32 v66, v66, v20, v21
	v_max3_f32 v66, v66, v22, v23
	v_max3_f32 v66, v66, v24, v25
	v_max3_f32 v66, v66, v26, v27
	v_max3_f32 v66, v66, v28, v29
	v_max3_f32 v66, v66, v30, v31
	v_max3_f32 v66, v66, v32, v33
	v_max3_f32 v66, v66, v34, v35
	v_max3_f32 v66, v66, v36, v37
	v_max3_f32 v66, v66, v38, v39
	v_max3_f32 v66, v66, v40, v41
	v_max3_f32 v66, v66, v42, v43
	v_max3_f32 v66, v66, v44, v45
	v_max3_f32 v66, v66, v46, v47
	v_mov_b32_e32 v67, v66
	s_nop 1
	v_permlane32_swap_b32_e32 v66, v67
	v_max_f32_e32 v67, v67, v67
	v_max_f32_e32 v66, v66, v66
	v_max_f32_e32 v66, v66, v67
	v_mov_b64_e32 v[14:15], s[22:23]
	v_add_f32_e32 v67, 0x7149f2ca, v66
	s_mov_b32 s18, 0x4138aa3b
	v_cmp_ge_f32_e32 vcc, s18, v67
	s_cmp_eq_u64 vcc, exec
	v_max_f32_e32 v55, 0xf149f2ca, v66
	s_cselect_b64 vcc, -1, 0
	v_cndmask_b32_e32 v140, v55, v54, vcc
	v_mul_f32_e32 v54, 0xbf800000, v140
	v_mov_b32_e32 v236, v54
	v_mov_b32_e32 v237, v54
	v_mov_b32_e32 v238, v54
	v_mov_b32_e32 v239, v54
	v_mov_b32_e32 v240, v54
	v_mov_b32_e32 v241, v54
	v_mov_b32_e32 v242, v54
	v_mov_b32_e32 v243, v54
	v_mov_b32_e32 v244, v54
	v_mov_b32_e32 v245, v54
	v_mov_b32_e32 v246, v54
	v_mov_b32_e32 v247, v54
	v_mov_b32_e32 v248, v54
	v_mov_b32_e32 v249, v54
	v_mov_b32_e32 v250, v54
	v_mov_b32_e32 v251, v54
	v_fmamk_f32 v16, v16, 0x3f800000, v54
	v_exp_f32_e32 v150, v16
	v_fmamk_f32 v16, v17, 0x3f800000, v54
	v_exp_f32_e32 v160, v16
	v_fmamk_f32 v16, v18, 0x3f800000, v54
	v_exp_f32_e32 v151, v16
	v_fmamk_f32 v16, v19, 0x3f800000, v54
	v_exp_f32_e32 v161, v16
	v_fmamk_f32 v16, v20, 0x3f800000, v54
	v_exp_f32_e32 v158, v16
	v_fmamk_f32 v16, v21, 0x3f800000, v54
	v_exp_f32_e32 v214, v16
	v_fmamk_f32 v16, v22, 0x3f800000, v54
	v_exp_f32_e32 v159, v16
	v_fmamk_f32 v16, v23, 0x3f800000, v54
	v_exp_f32_e32 v215, v16
	v_fmamk_f32 v16, v24, 0x3f800000, v54
	v_exp_f32_e32 v142, v16
	v_fmamk_f32 v16, v25, 0x3f800000, v54
	v_exp_f32_e32 v146, v16
	v_fmamk_f32 v16, v26, 0x3f800000, v54
	v_exp_f32_e32 v143, v16
	v_fmamk_f32 v16, v27, 0x3f800000, v54
	v_exp_f32_e32 v147, v16
	v_fmamk_f32 v16, v28, 0x3f800000, v54
	v_exp_f32_e32 v144, v16
	v_fmamk_f32 v16, v29, 0x3f800000, v54
	v_exp_f32_e32 v148, v16
	v_fmamk_f32 v16, v30, 0x3f800000, v54
	v_exp_f32_e32 v145, v16
	v_add3_u32 v16, v179, 0, v177
	v_add3_u32 v184, v16, v178, v176
	v_lshlrev_b32_e32 v16, 5, v48
	v_and_b32_e32 v16, 0x100, v16
	v_lshlrev_b32_e32 v17, 6, v73
	v_or3_b32 v18, v75, v16, v17
	v_or3_b32 v19, v72, v16, v17
	v_mov_b32_e32 v16, 0x88000
	v_pk_fma_f32 v[132:133], v[38:39], s[86:87], v[54:55] op_sel_hi:[1,0,0]
	v_sub_f32_e32 v38, 0xf149f2ca, v55
	v_mad_i64_i32 v[16:17], s[0:1], s47, v16, v[52:53]
	v_and_b32_e32 v20, 7, v70
	v_mul_f32_e32 v38, 0x3f800000, v38
	v_lshl_or_b32 v16, v20, 4, v16
	v_exp_f32_e32 v38, v38
	v_lshl_add_u64 v[154:155], s[96:97], 0, v[16:17]
	v_mov_b32_e32 v16, 0x110000
	v_pk_fma_f32 v[124:125], v[46:47], s[86:87], v[54:55] op_sel_hi:[1,0,0]
	v_pk_fma_f32 v[126:127], v[44:45], s[86:87], v[54:55] op_sel_hi:[1,0,0]
	v_pk_fma_f32 v[128:129], v[42:43], s[86:87], v[54:55] op_sel_hi:[1,0,0]
	v_pk_fma_f32 v[130:131], v[40:41], s[86:87], v[54:55] op_sel_hi:[1,0,0]
	v_pk_fma_f32 v[134:135], v[36:37], s[86:87], v[54:55] op_sel_hi:[1,0,0]
	v_pk_fma_f32 v[136:137], v[34:35], s[86:87], v[54:55] op_sel_hi:[1,0,0]
	v_pk_fma_f32 v[138:139], v[32:33], s[86:87], v[54:55] op_sel_hi:[1,0,0]
	v_fmac_f32_e32 v54, 0x3f800000, v31
	v_mad_i64_i32 v[16:17], s[0:1], s49, v16, v[50:51]
	v_and_b32_e32 v20, 15, v70
	v_exp_f32_e32 v149, v54
	v_lshl_or_b32 v16, v20, 4, v16
	s_add_i32 s49, 0, 0x4000
	v_lshl_add_u64 v[156:157], s[96:97], 0, v[16:17]
	v_add3_u32 v16, v179, s49, v177
	v_cndmask_b32_e64 v182, v38, 1.0, vcc
	s_mov_b32 s9, 0xe000
	v_add_u32_e32 v203, 0x8000, v18
	v_add_u32_e32 v204, 0x8000, v19
	v_add_u32_e32 v206, 0xc000, v18
	v_add_u32_e32 v207, 0xc000, v19
	v_add3_u32 v208, v16, v178, v176
	v_mov_b64_e32 v[62:63], v[14:15]
	v_mov_b64_e32 v[46:47], v[14:15]
	v_mov_b64_e32 v[30:31], v[14:15]
	v_add_u32_e32 v180, 0x10000, v76
	v_add_u32_e32 v181, 0, v80
	v_bitop3_b32 v198, v162, s9, v81 bitop3:0xde
	v_bitop3_b32 v200, v83, s9, v81 bitop3:0xde
	v_add_u32_e32 v202, 0, v74
	v_add_u32_e32 v205, 0x12000, v76
	v_bitop3_b32 v209, v71, s9, v81 bitop3:0xde
	v_bitop3_b32 v210, v84, s9, v81 bitop3:0xde
	v_mov_b32_e32 v170, 0
	s_mov_b32 s9, s8
	v_mov_b64_e32 v[60:61], v[12:13]
	v_mov_b64_e32 v[58:59], v[10:11]
	v_mov_b64_e32 v[56:57], v[8:9]
	v_mov_b64_e32 v[54:55], v[6:7]
	v_mov_b64_e32 v[52:53], v[4:5]
	v_mov_b64_e32 v[50:51], v[2:3]
	v_mov_b64_e32 v[48:49], v[0:1]
	v_mov_b64_e32 v[44:45], v[12:13]
	v_mov_b64_e32 v[42:43], v[10:11]
	v_mov_b64_e32 v[40:41], v[8:9]
	v_mov_b64_e32 v[38:39], v[6:7]
	v_mov_b64_e32 v[36:37], v[4:5]
	v_mov_b64_e32 v[34:35], v[2:3]
	v_mov_b64_e32 v[32:33], v[0:1]
	v_mov_b64_e32 v[28:29], v[12:13]
	v_mov_b64_e32 v[26:27], v[10:11]
	v_mov_b64_e32 v[24:25], v[8:9]
	v_mov_b64_e32 v[22:23], v[6:7]
	v_mov_b64_e32 v[20:21], v[4:5]
	v_mov_b64_e32 v[18:19], v[2:3]
	v_mov_b64_e32 v[16:17], v[0:1]
	s_mul_hi_u32 s1, s9, 0xaaaaaaab
	s_lshr_b32 s1, s1, 1
	s_mul_i32 s1, s1, 0xc000
	v_subrev_u32_e32 v190, s1, v184
	s_mul_hi_u32 s1, s51, 0xaaaaaaab
	s_mul_hi_u32 s0, s66, 0xaaaaaaab
	s_lshr_b32 s12, s1, 1
	s_lshr_b32 s0, s0, 1
	s_mul_i32 s1, s12, 0x6000
	s_mul_i32 s15, s0, 0x6000
	v_subrev_u32_e32 v64, s1, v198
	s_mul_i32 s0, s0, 0xc000
	v_subrev_u32_e32 v216, s15, v180
	v_subrev_u32_e32 v164, s1, v200
	v_subrev_u32_e32 v217, s0, v203
	v_subrev_u32_e32 v218, s0, v204
	v_subrev_u32_e32 v191, s1, v209
	v_subrev_u32_e32 v192, s1, v210
	s_waitcnt lgkmcnt(0)
	s_barrier
; #define SBAR() __builtin_amdgcn_sched_barrier(0)
; #define SLOAD(i, k0) do { sr_[i].vs0 = *reinterpret_cast<const bf16x8*>(&Vh[(size_t)((k0) + sr) * 128 + sc]); sr_[i].vs1 = *reinterpret_cast<const bf16x8*>(&Vh[(size_t)((k0) + 32 + sr) * 128 + sc]); \
;     sr_[i].ks0 = *reinterpret_cast<const bf16x8*>(&Kh[(size_t)((k0) + kr) * 64 + kc]); } while (0)
; DEV void finishSM(f32x16& p0, f32x16& p1, float alpha, float& l_reg, bf16x8& pa0, bf16x8& pa1, bf16x8& pa2, bf16x8& pa3) {
; #pragma unroll
;   for (int r = 0; r < 16; ++r) p1[r] = __builtin_amdgcn_exp2f(p1[r]);
;   float ps = 0;
; #pragma unroll
;   for (int r = 0; r < 16; ++r) ps += p0[r];
; #pragma unroll
;   for (int r = 0; r < 16; ++r) ps += p1[r];
;   { auto rr = __builtin_amdgcn_permlane32_swap(__float_as_uint(ps), __float_as_uint(ps), false, false);
;     ps = __uint_as_float(rr[0]) + __uint_as_float(rr[1]); }
;   l_reg = l_reg * alpha + ps;
;     ...
;   PK4(p0, 0, pa0); PK4(p0, 8, pa1); PK4(p1, 0, pa2); PK4(p1, 8, pa3);
; DEV void attn_pass(const u16* __restrict__ Qb, const u16* __restrict__ Kh, const u16* __restrict__ Vh, int seq, f32x16* o, float* rli) {
;     ...
;   for (int j = 1; j + 1 < NT; j += 2) {
;     const int bm1 = (j - 1) % 3, b0 = j % 3, b1 = (j + 1) % 3, b2 = (j + 2) % 3;
;     SBAR(); qkt(pB0, pB1, K_lds + b0 * AT_SHM_K, qr, r32, hi);
;     finishSM(pA0, pA1, alA, l_reg, pa0, pa1, pa2, pa3); SBAR();
;     SLOAD(SO, (j + 2) * 64); SBAR();
;     pv_d0(o, vb0 + bm1 * AT_SHM_V, pa0, pa1, pa2, pa3); partialSM(pB0, pB1, m_reg, mnB, alB);
.LBB0_70:
	v_add_u32_e32 v141, s14, v181
	v_add_u32_e32 v68, v141, v64
	ds_read_b128 v[64:67], v68
	ds_read_b128 v[68:71], v68 offset:4096
	v_add_u32_e32 v186, v141, v164
	ds_read_b128 v[164:167], v186
	ds_read_b128 v[186:189], v186 offset:4096
	s_waitcnt vmcnt(0)
	v_add_u32_e32 v72, s8, v202
	v_add_u32_e32 v73, v72, v218
	ds_write_b128 v73, v[116:119]
	v_add_u32_e32 v73, v72, v217
	s_add_i32 s13, s14, 0
	ds_write_b128 v73, v[112:115]
	v_add_u32_e32 v73, s13, v216
	ds_write_b128 v73, v[120:123]
	v_exp_f32_e32 v134, v134
	s_waitcnt lgkmcnt(6)
	v_mfma_f32_32x32x16_bf16 v[80:95], v[64:67], v[108:111], v[236:251]
	v_exp_f32_e32 v135, v135
	v_exp_f32_e32 v132, v132
	v_exp_f32_e32 v133, v133
	v_exp_f32_e32 v130, v130
	v_exp_f32_e32 v131, v131
	v_exp_f32_e32 v128, v128
	v_exp_f32_e32 v129, v129
	s_waitcnt lgkmcnt(5)
	v_mfma_f32_32x32x16_bf16 v[64:79], v[68:71], v[108:111], v[236:251]
	v_exp_f32_e32 v126, v126
	v_exp_f32_e32 v127, v127
	v_exp_f32_e32 v124, v124
	v_exp_f32_e32 v125, v125
	s_waitcnt lgkmcnt(4)
	v_mfma_f32_32x32x16_bf16 v[80:95], v[164:167], v[104:107], v[80:95]
	s_waitcnt lgkmcnt(3)
	v_mfma_f32_32x32x16_bf16 v[64:79], v[186:189], v[104:107], v[64:79]
	v_add_u32_e32 v186, v141, v191
	ds_read_b128 v[164:167], v186
	ds_read_b128 v[186:189], v186 offset:4096
	s_waitcnt lgkmcnt(1)
	v_mfma_f32_32x32x16_bf16 v[80:95], v[164:167], v[100:103], v[80:95]
	s_waitcnt lgkmcnt(0)
	v_mfma_f32_32x32x16_bf16 v[64:79], v[186:189], v[100:103], v[64:79]
	v_add_u32_e32 v186, v141, v192
	ds_read_b128 v[164:167], v186
	ds_read_b128 v[186:189], v186 offset:4096
	s_waitcnt lgkmcnt(1)
	v_mfma_f32_32x32x16_bf16 v[80:95], v[164:167], v[96:99], v[80:95]
	v_exp_f32_e32 v166, v136
	v_add_f32_e32 v136, v160, v150
	v_add_f32_e32 v136, v151, v136
	v_add_f32_e32 v136, v161, v136
	v_add_f32_e32 v136, v158, v136
	v_add_f32_e32 v136, v214, v136
	v_add_f32_e32 v136, v159, v136
	v_add_f32_e32 v136, v215, v136
	v_add_f32_e32 v136, v142, v136
	v_add_f32_e32 v136, v146, v136
	v_add_f32_e32 v136, v143, v136
	v_add_f32_e32 v136, v147, v136
	v_exp_f32_e32 v164, v138
	v_add_f32_e32 v136, v144, v136
	v_exp_f32_e32 v165, v139
	v_add_f32_e32 v136, v148, v136
	v_add_f32_e32 v136, v145, v136
	v_exp_f32_e32 v167, v137
	v_add_f32_e32 v136, v149, v136
	v_add_f32_e32 v136, v164, v136
	v_add_f32_e32 v136, v165, v136
	v_add_f32_e32 v136, v166, v136
	v_add_f32_e32 v136, v167, v136
	v_add_f32_e32 v136, v134, v136
	v_add_f32_e32 v136, v135, v136
	v_add_f32_e32 v136, v132, v136
	v_add_f32_e32 v136, v133, v136
	v_add_f32_e32 v136, v130, v136
	v_add_f32_e32 v136, v131, v136
	s_waitcnt lgkmcnt(0)
	v_mfma_f32_32x32x16_bf16 v[64:79], v[186:189], v[96:99], v[64:79]
	v_add_f32_e32 v136, v128, v136
	v_add_f32_e32 v136, v129, v136
	v_add_f32_e32 v136, v126, v136
	v_add_f32_e32 v136, v127, v136
	v_add_f32_e32 v136, v124, v136
	v_add_f32_e32 v211, v125, v136
	v_mov_b32_e32 v212, v211
	v_cvt_pk_bf16_f32 v136, v150, v160
	v_cvt_pk_bf16_f32 v138, v158, v214
	s_nop 1
	v_permlane32_swap_b32_e32 v211, v212
	v_cvt_pk_bf16_f32 v137, v151, v161
	v_cvt_pk_bf16_f32 v139, v159, v215
	v_permlane32_swap_b32_e32 v136, v138
	v_cvt_pk_bf16_f32 v142, v142, v146
	v_cvt_pk_bf16_f32 v143, v143, v147
	v_cvt_pk_bf16_f32 v144, v144, v148
	v_cvt_pk_bf16_f32 v145, v145, v149
	v_cvt_pk_bf16_f32 v146, v164, v165
	v_cvt_pk_bf16_f32 v147, v166, v167
	v_cvt_pk_bf16_f32 v148, v134, v135
	v_cvt_pk_bf16_f32 v149, v132, v133
	v_cvt_pk_bf16_f32 v164, v130, v131
	v_cvt_pk_bf16_f32 v165, v128, v129
	v_cvt_pk_bf16_f32 v166, v126, v127
	v_cvt_pk_bf16_f32 v167, v124, v125
	v_permlane32_swap_b32_e32 v137, v139
	v_permlane32_swap_b32_e32 v142, v144
	v_permlane32_swap_b32_e32 v143, v145
	v_permlane32_swap_b32_e32 v146, v148
	v_permlane32_swap_b32_e32 v147, v149
	v_permlane32_swap_b32_e32 v164, v166
	v_permlane32_swap_b32_e32 v165, v167
	v_lshl_add_u64 v[158:159], v[156:157], 0, s[82:83]
	v_add_co_u32_e32 v124, vcc, s94, v158
	v_lshl_add_u64 v[160:161], v[154:155], 0, s[82:83]
	s_nop 0
	v_addc_co_u32_e32 v125, vcc, 0, v159, vcc
	v_add_co_u32_e32 v128, vcc, s95, v158
	s_mov_b32 s0, 0x18606000
	s_nop 0
	v_addc_co_u32_e32 v129, vcc, 0, v159, vcc
	v_add_co_u32_e32 v132, vcc, s0, v160
	global_load_dwordx4 v[124:127], v[124:125], off
	s_nop 0
	global_load_dwordx4 v[128:131], v[128:129], off
	v_addc_co_u32_e32 v133, vcc, 0, v161, vcc
	global_load_dwordx4 v[132:135], v[132:133], off
	v_add_u32_e32 v150, s8, v190
	ds_read_b64_tr_b16 v[186:187], v150 offset:0
	ds_read_b64_tr_b16 v[188:189], v150 offset:0x800
	ds_read_b64_tr_b16 v[190:191], v150 offset:0x1000
	ds_read_b64_tr_b16 v[192:193], v150 offset:0x1800
	ds_read_b64_tr_b16 v[220:221], v150 offset:0x2000
	ds_read_b64_tr_b16 v[222:223], v150 offset:0x2800
	ds_read_b64_tr_b16 v[224:225], v150 offset:0x3000
	ds_read_b64_tr_b16 v[226:227], v150 offset:0x3800
	s_waitcnt lgkmcnt(0)
; #define SBAR() __builtin_amdgcn_sched_barrier(0)
; DEV void partialSM(f32x16& p0, f32x16& p1, float& m_reg, float& mn, float& alpha) {
;   constexpr float C = AT_SCALE * 1.4426950408889634f;
;   float pmax = p0[0];
; #pragma unroll
;   for (int r = 1; r < 16; ++r) pmax = fmaxf(pmax, p0[r]);
; #pragma unroll
;   for (int r = 0; r < 16; ++r) pmax = fmaxf(pmax, p1[r]);
;   { auto rr = __builtin_amdgcn_permlane32_swap(__float_as_uint(pmax), __float_as_uint(pmax), false, false);
;     pmax = fmaxf(__uint_as_float(rr[0]), __uint_as_float(rr[1])); }
;   if (__builtin_expect(__all(pmax - m_reg <= AT_THR / AT_SCALE), 1)) { mn = m_reg; alpha = 1.f; }
;   else { mn = fmaxf(m_reg, pmax); alpha = __builtin_amdgcn_exp2f((m_reg - mn) * C); m_reg = mn; }
; template <int OFF> DEV s16x4 tr_read(int vb) {
;   s16x4 r; asm volatile("ds_read_b64_tr_b16 %0, %1 offset:%2" : "=&v"(r) : "v"(vb), "i"(OFF) : "memory"); return r;
; }
; template <int D0> DEV void pv_one(f32x16& od, int vb, bf16x8 pa0, bf16x8 pa1, bf16x8 pa2, bf16x8 pa3) {
;   const s16x4 l0 = tr_read<v_rd_off(D0, 0, 0)>(vb), h0 = tr_read<v_rd_off(D0, 0, 1)>(vb), l1 = tr_read<v_rd_off(D0, 1, 0)>(vb), h1 = tr_read<v_rd_off(D0, 1, 1)>(vb);
;   const s16x4 l2 = tr_read<v_rd_off(D0, 2, 0)>(vb), h2 = tr_read<v_rd_off(D0, 2, 1)>(vb), l3 = tr_read<v_rd_off(D0, 3, 0)>(vb), h3 = tr_read<v_rd_off(D0, 3, 1)>(vb);
;   asm volatile("s_waitcnt lgkmcnt(0)" ::: "memory"); SBAR();
;     ...
;   od = __builtin_amdgcn_mfma_f32_32x32x16_bf16(pa0, PK(l0, h0), od, 0, 0, 0);
;   od = __builtin_amdgcn_mfma_f32_32x32x16_bf16(pa1, PK(l1, h1), od, 0, 0, 0);
;   od = __builtin_amdgcn_mfma_f32_32x32x16_bf16(pa2, PK(l2, h2), od, 0, 0, 0);
;   od = __builtin_amdgcn_mfma_f32_32x32x16_bf16(pa3, PK(l3, h3), od, 0, 0, 0);
;     ...
; }
; DEV void pv_d0(f32x16* o, int vb, bf16x8 pa0, bf16x8 pa1, bf16x8 pa2, bf16x8 pa3) {
;   pv_one<0>(o[0], vb, pa0, pa1, pa2, pa3); pv_one<1>(o[1], vb, pa0, pa1, pa2, pa3); pv_one<2>(o[2], vb, pa0, pa1, pa2, pa3); pv_one<3>(o[3], vb, pa0, pa1, pa2, pa3);
; }
	s_nop 0
	v_mfma_f32_32x32x16_bf16 v[0:15], v[136:139], v[186:189], v[0:15]
	ds_read_b64_tr_b16 v[186:187], v150 offset:0x200
	ds_read_b64_tr_b16 v[188:189], v150 offset:0xa00
	v_mfma_f32_32x32x16_bf16 v[0:15], v[142:145], v[190:193], v[0:15]
	ds_read_b64_tr_b16 v[190:191], v150 offset:0x1200
	ds_read_b64_tr_b16 v[192:193], v150 offset:0x1a00
	v_mfma_f32_32x32x16_bf16 v[0:15], v[146:149], v[220:223], v[0:15]
	ds_read_b64_tr_b16 v[220:221], v150 offset:0x2200
	ds_read_b64_tr_b16 v[222:223], v150 offset:0x2a00
	v_mfma_f32_32x32x16_bf16 v[0:15], v[164:167], v[224:227], v[0:15]
	ds_read_b64_tr_b16 v[224:225], v150 offset:0x3200
	ds_read_b64_tr_b16 v[226:227], v150 offset:0x3a00
	s_waitcnt lgkmcnt(0)
	v_mfma_f32_32x32x16_bf16 v[48:63], v[136:139], v[186:189], v[48:63]
	ds_read_b64_tr_b16 v[186:187], v150 offset:0x400
	ds_read_b64_tr_b16 v[188:189], v150 offset:0xc00
	v_mfma_f32_32x32x16_bf16 v[48:63], v[142:145], v[190:193], v[48:63]
	ds_read_b64_tr_b16 v[190:191], v150 offset:0x1400
	ds_read_b64_tr_b16 v[192:193], v150 offset:0x1c00
	v_mfma_f32_32x32x16_bf16 v[48:63], v[146:149], v[220:223], v[48:63]
	ds_read_b64_tr_b16 v[220:221], v150 offset:0x2400
	ds_read_b64_tr_b16 v[222:223], v150 offset:0x2c00
	v_mfma_f32_32x32x16_bf16 v[48:63], v[164:167], v[224:227], v[48:63]
	ds_read_b64_tr_b16 v[224:225], v150 offset:0x3400
	ds_read_b64_tr_b16 v[226:227], v150 offset:0x3c00
	s_waitcnt lgkmcnt(0)
	v_mfma_f32_32x32x16_bf16 v[32:47], v[136:139], v[186:189], v[32:47]
	ds_read_b64_tr_b16 v[186:187], v150 offset:0x600
	ds_read_b64_tr_b16 v[188:189], v150 offset:0xe00
	v_mfma_f32_32x32x16_bf16 v[32:47], v[142:145], v[190:193], v[32:47]
	ds_read_b64_tr_b16 v[190:191], v150 offset:0x1600
	ds_read_b64_tr_b16 v[192:193], v150 offset:0x1e00
	v_mfma_f32_32x32x16_bf16 v[32:47], v[146:149], v[220:223], v[32:47]
	ds_read_b64_tr_b16 v[220:221], v150 offset:0x2600
	ds_read_b64_tr_b16 v[222:223], v150 offset:0x2e00
	v_mfma_f32_32x32x16_bf16 v[32:47], v[164:167], v[224:227], v[32:47]
	ds_read_b64_tr_b16 v[224:225], v150 offset:0x3600
	ds_read_b64_tr_b16 v[226:227], v150 offset:0x3e00
	s_waitcnt lgkmcnt(0)
	v_mfma_f32_32x32x16_bf16 v[16:31], v[136:139], v[186:189], v[16:31]
	v_max_f32_e32 v136, v80, v81
	v_max3_f32 v137, v64, v65, v66
	v_max3_f32 v136, v136, v82, v83
	v_max3_f32 v137, v137, v67, v68
	v_max3_f32 v136, v136, v84, v85
	v_max3_f32 v137, v137, v69, v70
	v_max3_f32 v136, v136, v86, v87
	v_max3_f32 v137, v137, v71, v72
	v_mfma_f32_32x32x16_bf16 v[16:31], v[142:145], v[190:193], v[16:31]
	v_max3_f32 v136, v136, v88, v89
	v_max3_f32 v137, v137, v73, v74
	v_max3_f32 v136, v136, v90, v91
	v_max3_f32 v137, v137, v75, v76
	v_max3_f32 v136, v136, v92, v93
	v_max3_f32 v137, v137, v77, v78
	v_max3_f32 v136, v136, v94, v95
	v_max3_f32 v136, v136, v137, v79
	v_mfma_f32_32x32x16_bf16 v[16:31], v[146:149], v[220:223], v[16:31]
	v_mov_b32_e32 v137, v136
	s_nop 1
	v_permlane32_swap_b32_e32 v136, v137
	v_max_f32_e32 v136, v136, v137
	v_cmp_ge_f32_e32 vcc, s18, v136
	v_mfma_f32_32x32x16_bf16 v[16:31], v[164:167], v[224:227], v[16:31]
	s_cmp_eq_u64 vcc, exec
	s_cselect_b64 s[0:1], -1, 0
	s_cbranch_scc1 .Lattn_fast1
	v_max_f32_e32 v136, 0, v136
	v_exp_f32_e64 v137, -v136

; #define SBAR() __builtin_amdgcn_sched_barrier(0)
; #define SLOAD(i, k0) do { sr_[i].vs0 = *reinterpret_cast<const bf16x8*>(&Vh[(size_t)((k0) + sr) * 128 + sc]); sr_[i].vs1 = *reinterpret_cast<const bf16x8*>(&Vh[(size_t)((k0) + 32 + sr) * 128 + sc]); \
;     sr_[i].ks0 = *reinterpret_cast<const bf16x8*>(&Kh[(size_t)((k0) + kr) * 64 + kc]); } while (0)
; #define SWRITE(b, i) do { *(bf16x8*)(V_lds + (b) * AT_SHM_V + vst0) = sr_[i].vs0; *(bf16x8*)(V_lds + (b) * AT_SHM_V + vst1) = sr_[i].vs1; \
;     *(bf16x8*)(K_lds + (b) * AT_SHM_K + kst) = sr_[i].ks0; } while (0)
; #define SWAIT() asm volatile("s_waitcnt vmcnt(3)" ::: "memory")
; #define RESC(a) do { if (__any((a) < 1.f)) { if (hi == 0) al_l[r32] = (a); asm volatile("s_waitcnt lgkmcnt(0)" ::: "memory"); \
;     for (int d = 0; d < 4; ++d) for (int r = 0; r < 16; ++r) o[d][r] *= al_l[crow(r, hi)]; } } while (0)
; DEV void attn_pass(const u16* __restrict__ Qb, const u16* __restrict__ Kh, const u16* __restrict__ Vh, int seq, f32x16* o, float* rli) {
;     ...
;   for (int j = 1; j + 1 < NT; j += 2) {
;     const int bm1 = (j - 1) % 3, b0 = j % 3, b1 = (j + 1) % 3, b2 = (j + 2) % 3;
;     SBAR(); qkt(pB0, pB1, K_lds + b0 * AT_SHM_K, qr, r32, hi);
;     finishSM(pA0, pA1, alA, l_reg, pa0, pa1, pa2, pa3); SBAR();
;     SLOAD(SO, (j + 2) * 64); SBAR();
;     pv_d0(o, vb0 + bm1 * AT_SHM_V, pa0, pa1, pa2, pa3); partialSM(pB0, pB1, m_reg, mnB, alB);
;     SWAIT(); SWRITE(b1, SE);
;     RESC(alB); __syncthreads();
;     SBAR(); qkt(pA0, pA1, K_lds + b1 * AT_SHM_K, qr, r32, hi);
;     finishSM(pB0, pB1, alB, l_reg, pa0, pa1, pa2, pa3); SBAR();
;     if (j + 3 < NT) SLOAD(SE, (j + 3) * 64); SBAR();
;     pv_d0(o, vb0 + b0 * AT_SHM_V, pa0, pa1, pa2, pa3); partialSM(pA0, pA1, m_reg, mnA, alA);
;     SWAIT(); SWRITE(b2, SO);
;     RESC(alA); __syncthreads();
;   }
.LBB0_80:
	v_exp_f32_e32 v150, v80
	v_exp_f32_e32 v160, v81
	v_exp_f32_e32 v151, v82
	v_exp_f32_e32 v161, v83
	v_exp_f32_e32 v158, v84
	v_exp_f32_e32 v214, v85
	v_exp_f32_e32 v159, v86
	v_exp_f32_e32 v215, v87
	v_exp_f32_e32 v142, v88
	v_exp_f32_e32 v146, v89
	v_exp_f32_e32 v143, v90
	v_exp_f32_e32 v147, v91
	v_exp_f32_e32 v144, v92
	v_exp_f32_e32 v148, v93
	v_exp_f32_e32 v145, v94
	v_exp_f32_e32 v149, v95
	v_mov_b64_e32 v[138:139], v[64:65]
	v_add_f32_e32 v64, v211, v212
	s_mov_b64 s[0:1], 0x4000
	v_fmac_f32_e32 v64, v182, v170
	v_add_f32_e32 v170, v216, v217
	v_lshl_add_u64 v[154:155], v[154:155], 0, s[0:1]
	s_mov_b64 s[0:1], 0x8000
	v_mov_b64_e32 v[136:137], v[66:67]
	v_mov_b64_e32 v[134:135], v[68:69]
	v_mov_b64_e32 v[132:133], v[70:71]
	v_mov_b64_e32 v[130:131], v[72:73]
	v_mov_b64_e32 v[128:129], v[74:75]
	v_mov_b64_e32 v[126:127], v[76:77]
	v_mov_b64_e32 v[124:125], v[78:79]
	v_fmac_f32_e32 v170, v64, v213
	s_addk_i32 s14, 0x4000
	s_add_i32 s66, s66, 2
	s_add_i32 s45, s45, 2
	s_add_i32 s9, s9, 2
	s_add_i32 s8, s8, 0x8000
	v_lshl_add_u64 v[156:157], v[156:157], 0, s[0:1]
	s_add_i32 s50, s50, 2
	s_add_i32 s51, s51, 2
	s_mul_hi_u32 s1, s9, 0xaaaaaaab
	s_lshr_b32 s1, s1, 1
	s_mul_i32 s1, s1, 0xc000
	v_subrev_u32_e32 v190, s1, v184
	s_mul_hi_u32 s1, s51, 0xaaaaaaab
	s_mul_hi_u32 s0, s66, 0xaaaaaaab
	s_lshr_b32 s12, s1, 1
	s_lshr_b32 s0, s0, 1
	s_mul_i32 s1, s12, 0x6000
	s_mul_i32 s15, s0, 0x6000
	v_subrev_u32_e32 v64, s1, v198
	s_mul_i32 s0, s0, 0xc000
	v_subrev_u32_e32 v216, s15, v180
	v_subrev_u32_e32 v164, s1, v200
	v_subrev_u32_e32 v217, s0, v203
	v_subrev_u32_e32 v218, s0, v204
	v_subrev_u32_e32 v191, s1, v209
	v_subrev_u32_e32 v192, s1, v210
	s_and_b64 vcc, exec, s[10:11]
	s_waitcnt lgkmcnt(0)
	s_barrier
	s_cbranch_vccnz .LBB0_82
	v_mov_b32_e32 v182, v141
	s_branch .LBB0_70

; #define SBAR() __builtin_amdgcn_sched_barrier(0)
; #define RESC(a) do { if (__any((a) < 1.f)) { if (hi == 0) al_l[r32] = (a); asm volatile("s_waitcnt lgkmcnt(0)" ::: "memory"); \
;     for (int d = 0; d < 4; ++d) for (int r = 0; r < 16; ++r) o[d][r] *= al_l[crow(r, hi)]; } } while (0)
; DEV void partialSM(f32x16& p0, f32x16& p1, float& m_reg, float& mn, float& alpha) {
;     ...
;   float mnC = -mn * C;
; #pragma unroll
;   for (int r = 0; r < 16; ++r) p0[r] = fmaf(p0[r], C, mnC);
; #pragma unroll
;   for (int r = 0; r < 16; ++r) p1[r] = fmaf(p1[r], C, mnC);
; #pragma unroll
;   for (int r = 0; r < 16; ++r) p0[r] = __builtin_amdgcn_exp2f(p0[r]);
; }
; DEV void finishSM(f32x16& p0, f32x16& p1, float alpha, float& l_reg, bf16x8& pa0, bf16x8& pa1, bf16x8& pa2, bf16x8& pa3) {
; #pragma unroll
;   for (int r = 0; r < 16; ++r) p1[r] = __builtin_amdgcn_exp2f(p1[r]);
;   float ps = 0;
; #pragma unroll
;   for (int r = 0; r < 16; ++r) ps += p0[r];
; #pragma unroll
;   for (int r = 0; r < 16; ++r) ps += p1[r];
;   { auto rr = __builtin_amdgcn_permlane32_swap(__float_as_uint(ps), __float_as_uint(ps), false, false);
;     ps = __uint_as_float(rr[0]) + __uint_as_float(rr[1]); }
;   l_reg = l_reg * alpha + ps;
;     ...
;   PK4(p0, 0, pa0); PK4(p0, 8, pa1); PK4(p1, 0, pa2); PK4(p1, 8, pa3);
; DEV void attn_pass(const u16* __restrict__ Qb, const u16* __restrict__ Kh, const u16* __restrict__ Vh, int seq, f32x16* o, float* rli) {
;     ...
;   { const int bl = (NT - 1) % 3, bp = (NT - 2) % 3;
;     SBAR(); qkt(pB0, pB1, K_lds + bl * AT_SHM_K, qr, r32, hi);
;     finishSM(pA0, pA1, alA, l_reg, pa0, pa1, pa2, pa3); SBAR();
;     pv_d0(o, vb0 + bp * AT_SHM_V, pa0, pa1, pa2, pa3); partialSM(pB0, pB1, m_reg, mnB, alB);
;     RESC(alB);
;     finishSM(pB0, pB1, alB, l_reg, pa0, pa1, pa2, pa3); SBAR();
;     pv_d0(o, vb0 + bl * AT_SHM_V, pa0, pa1, pa2, pa3); }
.LBB0_87:
	v_cndmask_b32_e64 v99, v99, v140, s[0:1]
	v_mul_f32_e32 v99, 0xbf800000, v99
	v_fmamk_f32 v80, v80, 0x3f800000, v99
	v_fmamk_f32 v81, v81, 0x3f800000, v99
	v_fmamk_f32 v82, v82, 0x3f800000, v99
	v_fmamk_f32 v83, v83, 0x3f800000, v99
	v_fmamk_f32 v84, v84, 0x3f800000, v99
	v_fmamk_f32 v85, v85, 0x3f800000, v99
	v_fmamk_f32 v86, v86, 0x3f800000, v99
	v_fmamk_f32 v87, v87, 0x3f800000, v99
	v_fmamk_f32 v88, v88, 0x3f800000, v99
	v_fmamk_f32 v89, v89, 0x3f800000, v99
	v_fmamk_f32 v90, v90, 0x3f800000, v99
	v_fmamk_f32 v91, v91, 0x3f800000, v99
	v_fmamk_f32 v92, v92, 0x3f800000, v99
	v_fmamk_f32 v93, v93, 0x3f800000, v99
	v_fmamk_f32 v94, v94, 0x3f800000, v99
	v_fmamk_f32 v95, v95, 0x3f800000, v99
	v_fmamk_f32 v64, v64, 0x3f800000, v99
	v_fmamk_f32 v65, v65, 0x3f800000, v99
	v_fmamk_f32 v66, v66, 0x3f800000, v99
	v_fmamk_f32 v67, v67, 0x3f800000, v99
	v_fmamk_f32 v68, v68, 0x3f800000, v99
	v_fmamk_f32 v69, v69, 0x3f800000, v99
	v_fmamk_f32 v70, v70, 0x3f800000, v99
	v_fmamk_f32 v71, v71, 0x3f800000, v99
	v_fmamk_f32 v72, v72, 0x3f800000, v99
	v_fmamk_f32 v73, v73, 0x3f800000, v99
	v_fmamk_f32 v74, v74, 0x3f800000, v99
	v_fmamk_f32 v75, v75, 0x3f800000, v99
	v_fmamk_f32 v76, v76, 0x3f800000, v99
	v_fmamk_f32 v77, v77, 0x3f800000, v99
	v_fmamk_f32 v78, v78, 0x3f800000, v99
	v_fmac_f32_e32 v99, 0x3f800000, v79
	v_exp_f32_e32 v79, v80
	v_exp_f32_e32 v80, v81
	v_exp_f32_e32 v81, v82
	v_exp_f32_e32 v82, v83
	v_exp_f32_e32 v83, v84
	v_exp_f32_e32 v84, v85
	v_exp_f32_e32 v85, v86
	v_exp_f32_e32 v86, v87
	v_exp_f32_e32 v87, v88
	v_exp_f32_e32 v88, v89
	v_exp_f32_e32 v89, v90
	v_exp_f32_e32 v90, v91
	v_exp_f32_e32 v91, v92
	v_exp_f32_e32 v92, v93
	v_exp_f32_e32 v93, v94
	v_exp_f32_e32 v94, v95
	v_exp_f32_e32 v95, v64
	v_add_f32_e32 v64, v80, v79
	v_add_f32_e32 v64, v81, v64
	v_add_f32_e32 v64, v82, v64
	v_add_f32_e32 v64, v83, v64
	v_add_f32_e32 v64, v84, v64
	v_add_f32_e32 v64, v85, v64
	v_add_f32_e32 v64, v86, v64
	v_add_f32_e32 v64, v87, v64
	v_add_f32_e32 v64, v88, v64
	v_add_f32_e32 v64, v89, v64
	v_add_f32_e32 v64, v90, v64
	v_add_f32_e32 v64, v91, v64
	v_exp_f32_e32 v100, v65
	v_add_f32_e32 v64, v92, v64
	v_exp_f32_e32 v101, v66
	v_add_f32_e32 v64, v93, v64
	v_exp_f32_e32 v102, v67
	v_add_f32_e32 v64, v94, v64
	v_exp_f32_e32 v103, v68
	v_add_f32_e32 v64, v95, v64
	v_exp_f32_e32 v104, v69
	v_add_f32_e32 v64, v100, v64
	v_exp_f32_e32 v105, v70
	v_add_f32_e32 v64, v101, v64
	v_exp_f32_e32 v106, v71
	v_add_f32_e32 v64, v102, v64
	v_exp_f32_e32 v107, v72
	v_add_f32_e32 v64, v103, v64
	v_exp_f32_e32 v108, v73
	v_add_f32_e32 v64, v104, v64
	v_exp_f32_e32 v109, v74
	v_add_f32_e32 v64, v105, v64
	v_exp_f32_e32 v110, v75
	v_add_f32_e32 v64, v106, v64
	v_exp_f32_e32 v111, v76
	v_add_f32_e32 v64, v107, v64
	v_exp_f32_e32 v113, v77
	v_add_f32_e32 v64, v108, v64
	v_exp_f32_e32 v114, v78
	v_add_f32_e32 v64, v109, v64
	v_exp_f32_e32 v99, v99
	v_add_f32_e32 v64, v110, v64
	v_add_f32_e32 v64, v111, v64
	v_add_f32_e32 v64, v113, v64
	v_add_f32_e32 v64, v114, v64
	v_add_f32_e32 v64, v99, v64
	v_mov_b32_e32 v65, v64
	s_nop 1
	v_permlane32_swap_b32_e32 v64, v65
	v_cvt_pk_bf16_f32 v66, v79, v80
	v_cvt_pk_bf16_f32 v67, v81, v82
	v_cvt_pk_bf16_f32 v68, v83, v84
	v_cvt_pk_bf16_f32 v69, v85, v86
	v_cvt_pk_bf16_f32 v70, v87, v88
	v_cvt_pk_bf16_f32 v71, v89, v90
	v_cvt_pk_bf16_f32 v72, v91, v92
	v_cvt_pk_bf16_f32 v73, v93, v94
	v_cvt_pk_bf16_f32 v74, v95, v100
	v_cvt_pk_bf16_f32 v75, v101, v102
	v_cvt_pk_bf16_f32 v76, v103, v104
	v_cvt_pk_bf16_f32 v77, v105, v106
	v_cvt_pk_bf16_f32 v78, v107, v108
	v_cvt_pk_bf16_f32 v79, v109, v110
	v_cvt_pk_bf16_f32 v80, v111, v113
	v_cvt_pk_bf16_f32 v81, v114, v99
	s_nop 0
	v_permlane32_swap_b32_e32 v66, v68
	v_permlane32_swap_b32_e32 v67, v69
	v_permlane32_swap_b32_e32 v70, v72
	v_permlane32_swap_b32_e32 v71, v73
	v_permlane32_swap_b32_e32 v74, v76
	v_permlane32_swap_b32_e32 v75, v77
	v_permlane32_swap_b32_e32 v78, v80
	v_permlane32_swap_b32_e32 v79, v81
	s_lshl_b32 s51, s10, 14
	v_add_u32_e32 v94, s51, v112
	ds_read_b64_tr_b16 v[82:83], v94 offset:0
	ds_read_b64_tr_b16 v[84:85], v94 offset:0x800
	ds_read_b64_tr_b16 v[86:87], v94 offset:0x1000
	ds_read_b64_tr_b16 v[88:89], v94 offset:0x1800
	ds_read_b64_tr_b16 v[90:91], v94 offset:0x2000
	ds_read_b64_tr_b16 v[92:93], v94 offset:0x2800
	ds_read_b64_tr_b16 v[100:101], v94 offset:0x3000
	ds_read_b64_tr_b16 v[102:103], v94 offset:0x3800
	s_waitcnt lgkmcnt(0)
	s_nop 0
	v_mfma_f32_32x32x16_bf16 v[0:15], v[66:69], v[82:85], v[0:15]
	ds_read_b64_tr_b16 v[82:83], v94 offset:0x200
	ds_read_b64_tr_b16 v[84:85], v94 offset:0xa00
	v_mfma_f32_32x32x16_bf16 v[0:15], v[70:73], v[86:89], v[0:15]
	ds_read_b64_tr_b16 v[86:87], v94 offset:0x1200
	ds_read_b64_tr_b16 v[88:89], v94 offset:0x1a00
	v_mfma_f32_32x32x16_bf16 v[0:15], v[74:77], v[90:93], v[0:15]
	ds_read_b64_tr_b16 v[90:91], v94 offset:0x2200
	ds_read_b64_tr_b16 v[92:93], v94 offset:0x2a00
	v_mfma_f32_32x32x16_bf16 v[0:15], v[78:81], v[100:103], v[0:15]
	ds_read_b64_tr_b16 v[100:101], v94 offset:0x3200
	ds_read_b64_tr_b16 v[102:103], v94 offset:0x3a00
	s_waitcnt lgkmcnt(0)
	v_mfma_f32_32x32x16_bf16 v[48:63], v[66:69], v[82:85], v[48:63]
	ds_read_b64_tr_b16 v[82:83], v94 offset:0x400
	ds_read_b64_tr_b16 v[84:85], v94 offset:0xc00
	v_mfma_f32_32x32x16_bf16 v[48:63], v[70:73], v[86:89], v[48:63]
	ds_read_b64_tr_b16 v[86:87], v94 offset:0x1400
	ds_read_b64_tr_b16 v[88:89], v94 offset:0x1c00
	v_mfma_f32_32x32x16_bf16 v[48:63], v[74:77], v[90:93], v[48:63]
	ds_read_b64_tr_b16 v[90:91], v94 offset:0x2400
	ds_read_b64_tr_b16 v[92:93], v94 offset:0x2c00
	v_mfma_f32_32x32x16_bf16 v[48:63], v[78:81], v[100:103], v[48:63]
	ds_read_b64_tr_b16 v[100:101], v94 offset:0x3400
	ds_read_b64_tr_b16 v[102:103], v94 offset:0x3c00
	s_waitcnt lgkmcnt(0)
; DEV int crow(int r, int hi) { return (r & 3) + 8 * (r >> 2) + 4 * hi; }
; DEV void attn_pass(const u16* __restrict__ Qb, const u16* __restrict__ Kh, const u16* __restrict__ Vh, int seq, f32x16* o, float* rli) {
;     ...
;   if (hi == 0) li_l[r32] = l_reg; asm volatile("s_waitcnt lgkmcnt(0)" ::: "memory");
; #pragma unroll
;   for (int r = 0; r < 16; ++r) rli[r] = __builtin_amdgcn_rcpf(li_l[crow(r, hi)]);
;   __syncthreads();
; DEV void attn_item(const Params& p, int l, int b, int h, int qb, int dry) {
;     ...
;     int lz = 0; asm volatile("" : "+v"(lz));
;     float* sp = scr + (wid * 64) * 64 + lane + lz;
; #pragma unroll
;     for (int d0 = 0; d0 < 4; ++d0)
; #pragma unroll
;       for (int r = 0; r < 16; ++r) sp[(d0 * 16 + r) * 64] = o[d0][r] * rli[r];
	v_mfma_f32_32x32x16_bf16 v[32:47], v[66:69], v[82:85], v[32:47]
	ds_read_b64_tr_b16 v[82:83], v94 offset:0x600
	ds_read_b64_tr_b16 v[84:85], v94 offset:0xe00
	v_mfma_f32_32x32x16_bf16 v[32:47], v[70:73], v[86:89], v[32:47]
	ds_read_b64_tr_b16 v[86:87], v94 offset:0x1600
	ds_read_b64_tr_b16 v[88:89], v94 offset:0x1e00
	v_mfma_f32_32x32x16_bf16 v[32:47], v[74:77], v[90:93], v[32:47]
	ds_read_b64_tr_b16 v[90:91], v94 offset:0x2600
	ds_read_b64_tr_b16 v[92:93], v94 offset:0x2e00
	v_mfma_f32_32x32x16_bf16 v[32:47], v[78:81], v[100:103], v[32:47]
	ds_read_b64_tr_b16 v[100:101], v94 offset:0x3600
	ds_read_b64_tr_b16 v[102:103], v94 offset:0x3e00
	s_waitcnt lgkmcnt(0)
	v_mfma_f32_32x32x16_bf16 v[16:31], v[66:69], v[82:85], v[16:31]
	v_mfma_f32_32x32x16_bf16 v[16:31], v[70:73], v[86:89], v[16:31]
	v_mfma_f32_32x32x16_bf16 v[16:31], v[74:77], v[90:93], v[16:31]
	v_mfma_f32_32x32x16_bf16 v[16:31], v[78:81], v[100:103], v[16:31]
	s_and_saveexec_b64 s[0:1], s[6:7]
	v_add_f32_e32 v66, v96, v97
	v_fmac_f32_e32 v66, v170, v141
	v_add_f32_e32 v64, v64, v65
	v_fmac_f32_e32 v64, v66, v98
	ds_write_b32 v169, v64
	s_or_b64 exec, exec, s[0:1]
	s_waitcnt lgkmcnt(0)
	v_add_u32_e32 v72, v168, v162
	ds_read_b128 v[64:67], v72
	ds_read_b128 v[68:71], v72 offset:32
	v_and_b32_e32 v73, 63, v172
	v_lshlrev_b32_e32 v162, 2, v73
	s_movk_i32 s8, 0x2000
	s_waitcnt lgkmcnt(1)
	v_rcp_f32_e32 v74, v64
	v_rcp_f32_e32 v75, v65
	v_rcp_f32_e32 v76, v66
	v_rcp_f32_e32 v77, v67
	ds_read_b128 v[64:67], v72 offset:64
	s_waitcnt lgkmcnt(1)
	v_rcp_f32_e32 v78, v68
	v_rcp_f32_e32 v79, v69
	v_rcp_f32_e32 v80, v70
	v_rcp_f32_e32 v81, v71
	ds_read_b128 v[68:71], v72 offset:96
	s_waitcnt lgkmcnt(1)
	v_rcp_f32_e32 v82, v65
	v_lshlrev_b32_e32 v65, 6, v172
	v_rcp_f32_e32 v83, v66
	v_and_b32_e32 v66, 0xfffff000, v65
	v_rcp_f32_e32 v84, v67
	v_ashrrev_i32_e32 v67, 31, v66
	v_rcp_f32_e32 v72, v64
	v_mov_b32_e32 v64, v163
	v_lshl_add_u64 v[66:67], v[66:67], 2, s[56:57]
	s_waitcnt lgkmcnt(0)
	s_barrier
	v_lshl_add_u64 v[154:155], v[66:67], 0, v[162:163]
	v_ashrrev_i32_e32 v65, 31, v64
	v_lshl_add_u64 v[64:65], v[64:65], 2, v[154:155]
	v_mul_f32_e32 v0, v0, v74
	global_store_dword v[64:65], v0, off
	v_mul_f32_e32 v0, v1, v75
	global_store_dword v[64:65], v0, off offset:256
	v_mul_f32_e32 v0, v2, v76
	global_store_dword v[64:65], v0, off offset:512
	v_mul_f32_e32 v0, v3, v77
	global_store_dword v[64:65], v0, off offset:768
	v_mul_f32_e32 v0, v4, v78
	global_store_dword v[64:65], v0, off offset:1024
	v_mul_f32_e32 v0, v5, v79
	global_store_dword v[64:65], v0, off offset:1280
	v_mul_f32_e32 v0, v6, v80
	global_store_dword v[64:65], v0, off offset:1536
	v_mul_f32_e32 v0, v7, v81
	v_rcp_f32_e32 v68, v68
	global_store_dword v[64:65], v0, off offset:1792
	v_mul_f32_e32 v0, v8, v72
	v_rcp_f32_e32 v69, v69
	global_store_dword v[64:65], v0, off offset:2048
	v_mul_f32_e32 v0, v9, v82
	v_rcp_f32_e32 v70, v70
	global_store_dword v[64:65], v0, off offset:2304
	v_mul_f32_e32 v0, v10, v83
	v_rcp_f32_e32 v71, v71
	global_store_dword v[64:65], v0, off offset:2560
	v_mul_f32_e32 v0, v11, v84
	global_store_dword v[64:65], v0, off offset:2816
	v_mul_f32_e32 v0, v12, v68
	global_store_dword v[64:65], v0, off offset:3072
	v_mul_f32_e32 v0, v13, v69
	global_store_dword v[64:65], v0, off offset:3328
	v_mul_f32_e32 v0, v14, v70
	global_store_dword v[64:65], v0, off offset:3584
	v_mul_f32_e32 v0, v15, v71
	global_store_dword v[64:65], v0, off offset:3840
	v_add_co_u32_e32 v0, vcc, s87, v64
	v_mul_f32_e32 v4, v48, v74
	s_nop 0
	v_addc_co_u32_e32 v1, vcc, 0, v65, vcc
	v_add_co_u32_e32 v2, vcc, s8, v64
	s_or_b32 s6, s47, 1
	s_nop 0
	v_addc_co_u32_e32 v3, vcc, 0, v65, vcc
	global_store_dword v[2:3], v4, off offset:-4096
	v_mul_f32_e32 v4, v49, v75
	global_store_dword v[0:1], v4, off offset:256
	v_mul_f32_e32 v4, v50, v76
	global_store_dword v[0:1], v4, off offset:512
	v_mul_f32_e32 v4, v51, v77
	global_store_dword v[0:1], v4, off offset:768
	v_mul_f32_e32 v4, v52, v78
	global_store_dword v[0:1], v4, off offset:1024
	v_mul_f32_e32 v4, v53, v79
	global_store_dword v[0:1], v4, off offset:1280
	v_mul_f32_e32 v4, v54, v80
	global_store_dword v[0:1], v4, off offset:1536
	v_mul_f32_e32 v4, v55, v81
	global_store_dword v[0:1], v4, off offset:1792
	v_mul_f32_e32 v4, v56, v72
	global_store_dword v[0:1], v4, off offset:2048
	v_mul_f32_e32 v4, v57, v82
	global_store_dword v[0:1], v4, off offset:2304
	v_mul_f32_e32 v4, v58, v83
	global_store_dword v[0:1], v4, off offset:2560
	v_mul_f32_e32 v4, v59, v84
	global_store_dword v[0:1], v4, off offset:2816
	v_mul_f32_e32 v4, v60, v68
	global_store_dword v[0:1], v4, off offset:3072
	v_mul_f32_e32 v4, v61, v69
	global_store_dword v[0:1], v4, off offset:3328
	v_mul_f32_e32 v4, v62, v70
	global_store_dword v[0:1], v4, off offset:3584
	v_mul_f32_e32 v4, v63, v71
	global_store_dword v[0:1], v4, off offset:3840
	v_mul_f32_e32 v0, v32, v74
	global_store_dword v[2:3], v0, off
	v_mul_f32_e32 v0, v33, v75
	global_store_dword v[2:3], v0, off offset:256
	v_mul_f32_e32 v0, v34, v76
	global_store_dword v[2:3], v0, off offset:512
	v_mul_f32_e32 v0, v35, v77
	global_store_dword v[2:3], v0, off offset:768
	v_mul_f32_e32 v0, v36, v78
	global_store_dword v[2:3], v0, off offset:1024
	v_mul_f32_e32 v0, v37, v79
	global_store_dword v[2:3], v0, off offset:1280
	v_mul_f32_e32 v0, v38, v80
	global_store_dword v[2:3], v0, off offset:1536
	v_mul_f32_e32 v0, v39, v81
	global_store_dword v[2:3], v0, off offset:1792
	v_mul_f32_e32 v0, v40, v72
	global_store_dword v[2:3], v0, off offset:2048
	v_mul_f32_e32 v0, v41, v82
	global_store_dword v[2:3], v0, off offset:2304
	v_mul_f32_e32 v0, v42, v83
	global_store_dword v[2:3], v0, off offset:2560
; DEV int v_st(int k, int c) { const int kk = (k & ~0xC) | ((k & 4) << 1) | ((k & 8) >> 1); return ((kk >> 3) * 4 + (c >> 5)) * 512 + ((kk & 7) * 32 + (c & 31)) * 2; }
; DEV int v_rd_base(int lane) { return ((lane & 3) << 3) | (((lane >> 2) & 3) << 6) | (((lane >> 4) & 1) << 5) | (((lane >> 5) & 1) << 8); }
; #define SLOAD(i, k0) do { sr_[i].vs0 = *reinterpret_cast<const bf16x8*>(&Vh[(size_t)((k0) + sr) * 128 + sc]); sr_[i].vs1 = *reinterpret_cast<const bf16x8*>(&Vh[(size_t)((k0) + 32 + sr) * 128 + sc]); \
;     sr_[i].ks0 = *reinterpret_cast<const bf16x8*>(&Kh[(size_t)((k0) + kr) * 64 + kc]); } while (0)
; #define SWRITE(b, i) do { *(bf16x8*)(V_lds + (b) * AT_SHM_V + vst0) = sr_[i].vs0; *(bf16x8*)(V_lds + (b) * AT_SHM_V + vst1) = sr_[i].vs1; \
;     *(bf16x8*)(K_lds + (b) * AT_SHM_K + kst) = sr_[i].ks0; } while (0)
; DEV void attn_pass(const u16* __restrict__ Qb, const u16* __restrict__ Kh, const u16* __restrict__ Vh, int seq, f32x16* o, float* rli) {
;     ...
;   const u16* Qw = Qb + (size_t)(wid * 32 + r32) * 64 + hi * 8;
; #pragma unroll
;   for (int d0 = 0; d0 < 4; ++d0) qr[d0] = *reinterpret_cast<const bf16x8*>(Qw + d0 * 16);
;   const int sr = tid >> 4, sc = (tid & 15) * 8, vst0 = v_st(sr, sc), vst1 = v_st(32 + sr, sc);
;   const int kr = tid >> 3, kc = (tid & 7) * 8, kst = KSWZ64(kr, kc * 2);
;   const int vb0 = (int)(uintptr_t)(__attribute__((address_space(3))) char*)V_lds + v_rd_base(lane);
;   struct { bf16x8 vs0, vs1, ks0; } sr_[2];
;     ...
;   f32x16 pA0, pA1, pB0, pB1; float mnA, mnB, alA, alB; bf16x8 pa0, pa1, pa2, pa3; const int NT = seq / 64;
;   constexpr int SE = 0, SO = 1;
;   SLOAD(SE, 0); SLOAD(SO, 64);
;   asm volatile("s_waitcnt vmcnt(3)" ::: "memory"); SWRITE(0, SE); __syncthreads();
; DEV void attn_item(const Params& p, int l, int b, int h, int qb, int dry) {
;     ...
;       for (int r = 0; r < 16; ++r) sp[(d0 * 16 + r) * 64] = o[d0][r] * rli[r];
;   }
;   {
;     const int s = b * 16 + h * 2 + 1;
;     attn_pass(AQ + ((size_t)s * UU + uq) * 64, AK + (size_t)s * UU * 64, Vh, seq, o, rli);
	v_mul_f32_e32 v0, v43, v84
	global_store_dword v[2:3], v0, off offset:2816
	v_mul_f32_e32 v0, v44, v68
	global_store_dword v[2:3], v0, off offset:3072
	v_mul_f32_e32 v0, v45, v69
	global_store_dword v[2:3], v0, off offset:3328
	v_mul_f32_e32 v0, v46, v70
	global_store_dword v[2:3], v0, off offset:3584
	v_mul_f32_e32 v0, v47, v71
	global_store_dword v[2:3], v0, off offset:3840
	v_add_co_u32_e32 v0, vcc, s80, v64
	v_mul_f32_e32 v2, v16, v74
	s_nop 0
	v_addc_co_u32_e32 v1, vcc, 0, v65, vcc
	global_store_dword v[0:1], v2, off
	v_mul_f32_e32 v2, v17, v75
	global_store_dword v[0:1], v2, off offset:256
	v_mul_f32_e32 v2, v18, v76
	global_store_dword v[0:1], v2, off offset:512
	v_mul_f32_e32 v2, v19, v77
	global_store_dword v[0:1], v2, off offset:768
	v_mul_f32_e32 v2, v20, v78
	global_store_dword v[0:1], v2, off offset:1024
	v_mul_f32_e32 v2, v21, v79
	global_store_dword v[0:1], v2, off offset:1280
	v_mul_f32_e32 v2, v22, v80
	global_store_dword v[0:1], v2, off offset:1536
	v_mul_f32_e32 v2, v23, v81
	global_store_dword v[0:1], v2, off offset:1792
	v_mul_f32_e32 v2, v24, v72
	global_store_dword v[0:1], v2, off offset:2048
	v_mul_f32_e32 v2, v25, v82
	global_store_dword v[0:1], v2, off offset:2304
	v_mul_f32_e32 v2, v26, v83
	global_store_dword v[0:1], v2, off offset:2560
	v_mul_f32_e32 v2, v27, v84
	global_store_dword v[0:1], v2, off offset:2816
	v_mul_f32_e32 v2, v28, v68
	global_store_dword v[0:1], v2, off offset:3072
	v_mul_f32_e32 v2, v29, v69
	global_store_dword v[0:1], v2, off offset:3328
	v_mul_f32_e32 v2, v30, v70
	s_mul_i32 s0, s6, 0x1100
	global_store_dword v[0:1], v2, off offset:3584
	v_mul_f32_e32 v2, v31, v71
	s_mul_hi_i32 s1, s6, 0x1100
	s_add_u32 s0, s0, s46
	v_mov_b32_e32 v70, v252
	global_store_dword v[0:1], v2, off offset:3840
	s_addc_u32 s1, s1, 0
	s_lshl_b64 s[0:1], s[0:1], 7
	v_ashrrev_i32_e32 v48, 4, v70
	v_lshlrev_b32_e32 v20, 3, v70
	v_ashrrev_i32_e32 v49, 31, v48
	s_add_u32 s0, s36, s0
	v_and_b32_e32 v2, 0x78, v20
	v_add_u32_e32 v12, 32, v48
	v_lshlrev_b64 v[50:51], 8, v[48:49]
	s_addc_u32 s1, s37, s1
	s_mul_hi_i32 s7, s6, 0x88000
	s_mul_i32 s6, s6, 0x88000
	v_ashrrev_i32_e32 v14, 3, v70
	v_lshl_add_u64 v[0:1], s[64:65], 0, v[50:51]
	v_lshlrev_b32_e32 v2, 1, v2
	v_mov_b32_e32 v3, v163
	v_ashrrev_i32_e32 v13, 31, v12
	s_add_u32 s6, s38, s6
	v_lshl_add_u64 v[66:67], v[0:1], 0, v[2:3]
	v_lshlrev_b64 v[0:1], 8, v[12:13]
	v_ashrrev_i32_e32 v15, 31, v14
	s_addc_u32 s7, s39, s7
	v_lshlrev_b32_e32 v71, 4, v70
	v_lshl_add_u64 v[0:1], s[64:65], 0, v[0:1]
	v_lshlrev_b64 v[52:53], 7, v[14:15]
	v_and_b32_e32 v16, 0x70, v71
	v_lshl_add_u64 v[4:5], v[0:1], 0, v[2:3]
	v_lshl_add_u64 v[8:9], s[6:7], 0, v[52:53]
	v_mov_b32_e32 v17, v163
	global_load_dwordx4 v[0:3], v[66:67], off
	s_nop 0
	global_load_dwordx4 v[4:7], v[4:5], off
	v_lshl_add_u64 v[68:69], v[8:9], 0, v[16:17]
	global_load_dwordx4 v[8:11], v[68:69], off
	v_ashrrev_i32_e32 v13, 1, v70
	v_bfi_b32 v18, s68, v13, v70
	v_ashrrev_i32_e32 v19, 31, v18
	v_lshlrev_b64 v[18:19], 7, v[18:19]
	v_lshrrev_b32_e32 v13, 1, v70
	v_lshl_add_u64 v[18:19], s[0:1], 0, v[18:19]
	v_and_b32_e32 v156, 16, v13
	v_mov_b32_e32 v157, v163
	v_lshl_add_u64 v[18:19], v[18:19], 0, v[156:157]
	global_load_dwordx4 v[108:111], v[18:19], off
	global_load_dwordx4 v[104:107], v[18:19], off offset:32
	global_load_dwordx4 v[100:103], v[18:19], off offset:64
	global_load_dwordx4 v[96:99], v[18:19], off offset:96
	v_and_b32_e32 v13, 0xfffff0, v48
	v_lshlrev_b32_e32 v15, 1, v48
	v_and_or_b32 v13, v15, 8, v13
	v_lshrrev_b32_e32 v13, 1, v13
	v_bfe_u32 v17, v20, 5, 2
	v_lshrrev_b32_e32 v15, 1, v48
	v_or_b32_e32 v13, v13, v17
	v_and_b32_e32 v73, 3, v48
	v_lshlrev_b32_e32 v72, 9, v13
	v_and_or_b32 v13, v15, 4, v73
	v_and_b32_e32 v15, 0xfffff0, v12
	v_lshlrev_b32_e32 v12, 1, v12
	v_and_or_b32 v12, v12, 8, v15
	v_lshrrev_b32_e32 v12, 1, v12
	v_or_b32_e32 v12, v12, v17
	v_lshlrev_b32_e32 v13, 6, v13
	v_and_b32_e32 v74, 48, v71
	v_lshlrev_b32_e32 v75, 9, v12
	v_or3_b32 v18, v72, v13, v74
	v_or3_b32 v17, v75, v13, v74
	v_lshlrev_b32_e32 v12, 7, v14
	v_and_b32_e32 v13, 0x70, v70
	v_bitop3_b32 v76, v16, v12, v13 bitop3:0xde
	v_add_co_u32_e32 v12, vcc, s75, v66
	s_movk_i32 s0, 0x6000
	s_nop 0
	v_addc_co_u32_e32 v13, vcc, 0, v67, vcc
	global_load_dwordx4 v[54:57], v[12:13], off
	v_add_co_u32_e32 v12, vcc, s0, v66
	v_and_b32_e32 v49, 31, v70
	s_nop 0
	v_addc_co_u32_e32 v13, vcc, 0, v67, vcc
	v_add_co_u32_e32 v14, vcc, s8, v68
	v_lshlrev_b32_e32 v80, 7, v49
	s_nop 0
	v_addc_co_u32_e32 v15, vcc, 0, v69, vcc
	global_load_dwordx4 v[58:61], v[12:13], off
	global_load_dwordx4 v[62:65], v[14:15], off
	v_and_b32_e32 v81, 0x70, v20
	v_add_u32_e32 v77, 0, v18
	v_add_u32_e32 v78, 0, v17
	v_bitop3_b32 v175, v156, v80, v81 bitop3:0xde
	s_waitcnt vmcnt(3)
	v_add_u32_e32 v79, 0, v76
	v_or_b32_e32 v83, 32, v156
	v_bitop3_b32 v178, v83, v80, v81 bitop3:0xde
	v_and_b32_e32 v82, 63, v70
	s_mov_b32 s0, 0xa000
	v_and_b32_e32 v180, 0xc0, v71
	v_or_b32_e32 v71, 64, v156
	v_bitop3_b32 v177, v71, v80, v81 bitop3:0xde
	v_or_b32_e32 v84, 0x60, v156
	v_bitop3_b32 v176, v84, v80, v81 bitop3:0xde
	s_mov_b32 s8, 0
	s_mov_b32 s9, s8
	s_mov_b32 s10, s8
	s_mov_b32 s11, s8
	s_mov_b32 s12, s8
	s_mov_b32 s13, s8
	s_mov_b32 s14, s8
	s_mov_b32 s15, s8
	s_mov_b32 s16, s8
	s_mov_b32 s17, s8
	s_waitcnt vmcnt(9)
	ds_write_b128 v77, v[0:3]
	s_waitcnt vmcnt(8)
	ds_write_b128 v78, v[4:7]
	v_add_u32_e32 v4, 0, v175
	v_and_b32_e32 v5, 0x3fffffc0, v70
	s_waitcnt vmcnt(7)
	ds_write_b128 v79, v[8:11] offset:49152
	s_waitcnt lgkmcnt(0)
	s_barrier
; #define SLOAD(i, k0) do { sr_[i].vs0 = *reinterpret_cast<const bf16x8*>(&Vh[(size_t)((k0) + sr) * 128 + sc]); sr_[i].vs1 = *reinterpret_cast<const bf16x8*>(&Vh[(size_t)((k0) + 32 + sr) * 128 + sc]); \
;     sr_[i].ks0 = *reinterpret_cast<const bf16x8*>(&Kh[(size_t)((k0) + kr) * 64 + kc]); } while (0)
; #define SWRITE(b, i) do { *(bf16x8*)(V_lds + (b) * AT_SHM_V + vst0) = sr_[i].vs0; *(bf16x8*)(V_lds + (b) * AT_SHM_V + vst1) = sr_[i].vs1; \
;     *(bf16x8*)(K_lds + (b) * AT_SHM_K + kst) = sr_[i].ks0; } while (0)
; #define SWAIT() asm volatile("s_waitcnt vmcnt(3)" ::: "memory")
; DEV void partialSM(f32x16& p0, f32x16& p1, float& m_reg, float& mn, float& alpha) {
;   constexpr float C = AT_SCALE * 1.4426950408889634f;
;   float pmax = p0[0];
; #pragma unroll
;   for (int r = 1; r < 16; ++r) pmax = fmaxf(pmax, p0[r]);
; #pragma unroll
;   for (int r = 0; r < 16; ++r) pmax = fmaxf(pmax, p1[r]);
;   { auto rr = __builtin_amdgcn_permlane32_swap(__float_as_uint(pmax), __float_as_uint(pmax), false, false);
;     pmax = fmaxf(__uint_as_float(rr[0]), __uint_as_float(rr[1])); }
;   if (__builtin_expect(__all(pmax - m_reg <= AT_THR / AT_SCALE), 1)) { mn = m_reg; alpha = 1.f; }
;   else { mn = fmaxf(m_reg, pmax); alpha = __builtin_amdgcn_exp2f((m_reg - mn) * C); m_reg = mn; }
;   float mnC = -mn * C;
; #pragma unroll
;   for (int r = 0; r < 16; ++r) p0[r] = fmaf(p0[r], C, mnC);
; #pragma unroll
;   for (int r = 0; r < 16; ++r) p1[r] = fmaf(p1[r], C, mnC);
; #pragma unroll
;   for (int r = 0; r < 16; ++r) p0[r] = __builtin_amdgcn_exp2f(p0[r]);
; }
; DEV void attn_pass(const u16* __restrict__ Qb, const u16* __restrict__ Kh, const u16* __restrict__ Vh, int seq, f32x16* o, float* rli) {
;     ...
;   SLOAD(SE, 0); SLOAD(SO, 64);
;   asm volatile("s_waitcnt vmcnt(3)" ::: "memory"); SWRITE(0, SE); __syncthreads();
;   if (2 < NT) SLOAD(SE, 2 * 64);
;   qkt(pA0, pA1, K_lds, qr, r32, hi); partialSM(pA0, pA1, m_reg, mnA, alA);
;   SWAIT(); SWRITE(1, SO); __syncthreads();
	ds_read_b128 v[0:3], v4 offset:49152
	v_lshl_add_u32 v157, v5, 2, s48
	ds_read_b128 v[4:7], v4 offset:53248
	v_add_u32_e32 v8, 0, v178
	s_waitcnt vmcnt(6) lgkmcnt(1)
	v_mfma_f32_32x32x16_bf16 v[16:31], v[0:3], v[108:111], 0
	ds_read_b128 v[0:3], v8 offset:49152
	s_mov_b32 s18, s8
	s_mov_b32 s19, s8
	s_mov_b32 s20, s8
	s_mov_b32 s21, s8
	s_mov_b32 s22, s8
	s_mov_b32 s23, s8
	s_waitcnt lgkmcnt(1)
	v_mfma_f32_32x32x16_bf16 v[32:47], v[4:7], v[108:111], 0
	v_lshlrev_b32_e32 v4, 3, v82
	v_lshlrev_b32_e32 v5, 1, v70
	v_and_b32_e32 v179, 24, v4
	v_and_b32_e32 v181, 32, v5
	v_and_b32_e32 v182, 0x100, v4
	ds_read_b128 v[4:7], v8 offset:53248
	v_add_co_u32_e32 v8, vcc, s75, v68
	s_waitcnt vmcnt(5) lgkmcnt(0)
	v_mfma_f32_32x32x16_bf16 v[32:47], v[4:7], v[104:107], v[32:47]
	v_addc_co_u32_e32 v9, vcc, 0, v69, vcc
	v_add_co_u32_e32 v10, vcc, s0, v66
	s_mov_b32 s0, 0x8000
	s_nop 0
	v_addc_co_u32_e32 v11, vcc, 0, v67, vcc
	v_add_co_u32_e32 v4, vcc, s0, v66
	v_add_u32_e32 v6, 0, v177
	s_nop 0
	v_addc_co_u32_e32 v5, vcc, 0, v67, vcc
	v_mfma_f32_32x32x16_bf16 v[16:31], v[0:3], v[104:107], v[16:31]
	ds_read_b128 v[0:3], v6 offset:49152
	global_load_dwordx4 v[120:123], v[8:9], off
	global_load_dwordx4 v[112:115], v[10:11], off
	global_load_dwordx4 v[116:119], v[4:5], off
	v_add_u32_e32 v8, 0, v176
	ds_read_b128 v[4:7], v6 offset:53248
	ds_read_b128 v[66:69], v8 offset:53248
	v_lshl_add_u32 v173, v49, 2, v157
	s_waitcnt vmcnt(7) lgkmcnt(2)
	v_mfma_f32_32x32x16_bf16 v[16:31], v[0:3], v[100:103], v[16:31]
	ds_read_b128 v[0:3], v8 offset:49152
	s_waitcnt vmcnt(3)
	s_waitcnt vmcnt(5)
	ds_write_b128 v77, v[54:57] offset:16384
	s_waitcnt vmcnt(4)
	ds_write_b128 v78, v[58:61] offset:16384
	s_waitcnt vmcnt(3)
	ds_write_b128 v79, v[62:65] offset:57344
	v_mov_b32_e32 v54, 0xf149f2ca
	s_mov_b32 s0, 0x10000
	s_mov_b32 s1, 0xe000
	s_mov_b32 s46, 2
	s_waitcnt lgkmcnt(5)
	v_mfma_f32_32x32x16_bf16 v[32:47], v[4:7], v[100:103], v[32:47]
	s_mov_b32 s47, 1
	s_mov_b32 s48, 4
	s_mov_b32 s64, 3
	v_cmp_gt_u32_e64 s[6:7], 32, v82
	v_add_u32_e32 v183, 0x10000, v76
	v_add_u32_e32 v184, 0, v80
	v_bitop3_b32 v198, v156, s0, v81 bitop3:0xde
	s_waitcnt lgkmcnt(3)
	v_mfma_f32_32x32x16_bf16 v[16:31], v[0:3], v[96:99], v[16:31]
	v_mov_b64_e32 v[0:1], s[8:9]
	v_mov_b64_e32 v[2:3], s[10:11]
	v_mov_b64_e32 v[4:5], s[12:13]
	v_mov_b64_e32 v[6:7], s[14:15]
	v_mov_b64_e32 v[8:9], s[16:17]
	v_mov_b64_e32 v[10:11], s[18:19]
	v_mov_b64_e32 v[12:13], s[20:21]
	v_mfma_f32_32x32x16_bf16 v[32:47], v[66:69], v[96:99], v[32:47]
	s_nop 3
	v_max_f32_e32 v66, v17, v17
	v_max_f32_e32 v67, v16, v16
	v_max_f32_e32 v66, v67, v66
	v_max3_f32 v66, v66, v18, v19
	v_max3_f32 v66, v66, v20, v21
	v_max3_f32 v66, v66, v22, v23
	v_max3_f32 v66, v66, v24, v25
	v_max3_f32 v66, v66, v26, v27
	v_max3_f32 v66, v66, v28, v29
	v_max3_f32 v66, v66, v30, v31
	v_max3_f32 v66, v66, v32, v33
	v_max3_f32 v66, v66, v34, v35
	v_max3_f32 v66, v66, v36, v37
	v_max3_f32 v66, v66, v38, v39
	v_max3_f32 v66, v66, v40, v41
	v_max3_f32 v66, v66, v42, v43
	v_max3_f32 v66, v66, v44, v45
	v_max3_f32 v66, v66, v46, v47
	v_mov_b32_e32 v67, v66
	s_nop 1
	v_permlane32_swap_b32_e32 v66, v67
	v_max_f32_e32 v67, v67, v67
	v_max_f32_e32 v66, v66, v66
	v_max_f32_e32 v66, v66, v67
	v_mov_b64_e32 v[14:15], s[22:23]
	v_add_f32_e32 v67, 0x7149f2ca, v66
	s_mov_b32 s18, 0x4138aa3b
	v_cmp_ge_f32_e32 vcc, s18, v67
	s_cmp_eq_u64 vcc, exec
	v_max_f32_e32 v55, 0xf149f2ca, v66
	s_cselect_b64 vcc, -1, 0
	v_cndmask_b32_e32 v140, v55, v54, vcc
	v_mul_f32_e32 v54, 0xbf800000, v140
	v_mov_b32_e32 v236, v54
	v_mov_b32_e32 v237, v54
	v_mov_b32_e32 v238, v54
	v_mov_b32_e32 v239, v54
	v_mov_b32_e32 v240, v54
	v_mov_b32_e32 v241, v54
	v_mov_b32_e32 v242, v54
	v_mov_b32_e32 v243, v54
	v_mov_b32_e32 v244, v54
	v_mov_b32_e32 v245, v54
	v_mov_b32_e32 v246, v54
	v_mov_b32_e32 v247, v54
	v_mov_b32_e32 v248, v54
	v_mov_b32_e32 v249, v54
	v_mov_b32_e32 v250, v54
	v_mov_b32_e32 v251, v54
	v_fmamk_f32 v16, v16, 0x3f800000, v54
	v_exp_f32_e32 v150, v16
	v_fmamk_f32 v16, v17, 0x3f800000, v54
	v_exp_f32_e32 v170, v16
	v_fmamk_f32 v16, v18, 0x3f800000, v54
	v_exp_f32_e32 v151, v16
	v_fmamk_f32 v16, v19, 0x3f800000, v54
	v_exp_f32_e32 v171, v16
	v_fmamk_f32 v16, v20, 0x3f800000, v54
	v_exp_f32_e32 v168, v16
	v_fmamk_f32 v16, v21, 0x3f800000, v54
	v_exp_f32_e32 v217, v16
	v_fmamk_f32 v16, v22, 0x3f800000, v54
	v_exp_f32_e32 v169, v16
	v_fmamk_f32 v16, v23, 0x3f800000, v54
	v_exp_f32_e32 v218, v16
	v_fmamk_f32 v16, v24, 0x3f800000, v54
	v_exp_f32_e32 v142, v16
	v_fmamk_f32 v16, v25, 0x3f800000, v54
	v_exp_f32_e32 v146, v16
	v_fmamk_f32 v16, v26, 0x3f800000, v54
	v_exp_f32_e32 v143, v16
	v_fmamk_f32 v16, v27, 0x3f800000, v54
	v_exp_f32_e32 v147, v16
	v_fmamk_f32 v16, v28, 0x3f800000, v54
	v_exp_f32_e32 v144, v16
	v_fmamk_f32 v16, v29, 0x3f800000, v54
	v_exp_f32_e32 v148, v16
	v_fmamk_f32 v16, v30, 0x3f800000, v54
	v_exp_f32_e32 v145, v16
	v_add3_u32 v16, v182, 0, v180
	v_add3_u32 v199, v16, v181, v179
	v_lshlrev_b32_e32 v16, 5, v48
	v_pk_fma_f32 v[132:133], v[38:39], s[86:87], v[54:55] op_sel_hi:[1,0,0]
	v_sub_f32_e32 v38, 0xf149f2ca, v55
	v_and_b32_e32 v16, 0x100, v16
	v_lshlrev_b32_e32 v17, 6, v73
	v_and_b32_e32 v18, 7, v70
	v_mul_f32_e32 v38, 0x3f800000, v38
	v_or3_b32 v20, v75, v16, v17
	v_or3_b32 v21, v72, v16, v17
	v_lshl_add_u64 v[16:17], s[62:63], 0, v[52:53]
	v_lshlrev_b32_e32 v18, 4, v18
	v_mov_b32_e32 v19, v163
	v_exp_f32_e32 v38, v38
	v_lshl_add_u64 v[16:17], v[16:17], 0, v[18:19]
	v_and_b32_e32 v18, 15, v70
	v_pk_fma_f32 v[124:125], v[46:47], s[86:87], v[54:55] op_sel_hi:[1,0,0]
	v_pk_fma_f32 v[126:127], v[44:45], s[86:87], v[54:55] op_sel_hi:[1,0,0]
; #define SBAR() __builtin_amdgcn_sched_barrier(0)
; #define SLOAD(i, k0) do { sr_[i].vs0 = *reinterpret_cast<const bf16x8*>(&Vh[(size_t)((k0) + sr) * 128 + sc]); sr_[i].vs1 = *reinterpret_cast<const bf16x8*>(&Vh[(size_t)((k0) + 32 + sr) * 128 + sc]); \
;     sr_[i].ks0 = *reinterpret_cast<const bf16x8*>(&Kh[(size_t)((k0) + kr) * 64 + kc]); } while (0)
; #define SWRITE(b, i) do { *(bf16x8*)(V_lds + (b) * AT_SHM_V + vst0) = sr_[i].vs0; *(bf16x8*)(V_lds + (b) * AT_SHM_V + vst1) = sr_[i].vs1; \
;     *(bf16x8*)(K_lds + (b) * AT_SHM_K + kst) = sr_[i].ks0; } while (0)
; #define SWAIT() asm volatile("s_waitcnt vmcnt(3)" ::: "memory")
; DEV void finishSM(f32x16& p0, f32x16& p1, float alpha, float& l_reg, bf16x8& pa0, bf16x8& pa1, bf16x8& pa2, bf16x8& pa3) {
; #pragma unroll
;   for (int r = 0; r < 16; ++r) p1[r] = __builtin_amdgcn_exp2f(p1[r]);
;   float ps = 0;
; #pragma unroll
;   for (int r = 0; r < 16; ++r) ps += p0[r];
; #pragma unroll
;   for (int r = 0; r < 16; ++r) ps += p1[r];
;   { auto rr = __builtin_amdgcn_permlane32_swap(__float_as_uint(ps), __float_as_uint(ps), false, false);
;     ps = __uint_as_float(rr[0]) + __uint_as_float(rr[1]); }
;   l_reg = l_reg * alpha + ps;
; DEV void attn_pass(const u16* __restrict__ Qb, const u16* __restrict__ Kh, const u16* __restrict__ Vh, int seq, f32x16* o, float* rli) {
;     ...
;   qkt(pA0, pA1, K_lds, qr, r32, hi); partialSM(pA0, pA1, m_reg, mnA, alA);
;   SWAIT(); SWRITE(1, SO); __syncthreads();
; #pragma unroll 1
;   for (int j = 1; j + 1 < NT; j += 2) {
;     const int bm1 = (j - 1) % 3, b0 = j % 3, b1 = (j + 1) % 3, b2 = (j + 2) % 3;
;     SBAR(); qkt(pB0, pB1, K_lds + b0 * AT_SHM_K, qr, r32, hi);
;     finishSM(pA0, pA1, alA, l_reg, pa0, pa1, pa2, pa3); SBAR();
;     SLOAD(SO, (j + 2) * 64); SBAR();
;     pv_d0(o, vb0 + bm1 * AT_SHM_V, pa0, pa1, pa2, pa3); partialSM(pB0, pB1, m_reg, mnB, alB);
	v_pk_fma_f32 v[128:129], v[42:43], s[86:87], v[54:55] op_sel_hi:[1,0,0]
	v_pk_fma_f32 v[130:131], v[40:41], s[86:87], v[54:55] op_sel_hi:[1,0,0]
	v_pk_fma_f32 v[134:135], v[36:37], s[86:87], v[54:55] op_sel_hi:[1,0,0]
	v_pk_fma_f32 v[136:137], v[34:35], s[86:87], v[54:55] op_sel_hi:[1,0,0]
	v_pk_fma_f32 v[138:139], v[32:33], s[86:87], v[54:55] op_sel_hi:[1,0,0]
	v_fmac_f32_e32 v54, 0x3f800000, v31
	v_lshl_add_u64 v[158:159], s[96:97], 0, v[16:17]
	v_lshl_add_u64 v[16:17], s[52:53], 0, v[50:51]
	v_lshlrev_b32_e32 v18, 4, v18
	v_exp_f32_e32 v149, v54
	v_lshl_add_u64 v[16:17], v[16:17], 0, v[18:19]
	v_lshl_add_u64 v[160:161], s[96:97], 0, v[16:17]
	v_add3_u32 v16, v182, s49, v180
	v_cndmask_b32_e64 v185, v38, 1.0, vcc
	v_add_u32_e32 v206, 0x8000, v20
	v_add_u32_e32 v207, 0x8000, v21
	v_add_u32_e32 v209, 0xc000, v20
	v_add_u32_e32 v210, 0xc000, v21
	v_add3_u32 v211, v16, v181, v179
	v_mov_b64_e32 v[62:63], v[14:15]
	v_mov_b64_e32 v[46:47], v[14:15]
	v_mov_b64_e32 v[30:31], v[14:15]
	v_bitop3_b32 v200, v83, s0, v81 bitop3:0xde
	v_bitop3_b32 v201, v156, s1, v81 bitop3:0xde
	v_bitop3_b32 v202, v71, s0, v81 bitop3:0xde
	v_bitop3_b32 v203, v83, s1, v81 bitop3:0xde
	v_bitop3_b32 v204, v84, s0, v81 bitop3:0xde
	v_add_u32_e32 v205, 0, v74
	v_add_u32_e32 v208, 0x12000, v76
	v_bitop3_b32 v212, v71, s1, v81 bitop3:0xde
	v_bitop3_b32 v213, v84, s1, v81 bitop3:0xde
	v_mov_b32_e32 v174, 0
	v_mov_b64_e32 v[60:61], v[12:13]
	v_mov_b64_e32 v[58:59], v[10:11]
	v_mov_b64_e32 v[56:57], v[8:9]
	v_mov_b64_e32 v[54:55], v[6:7]
	v_mov_b64_e32 v[52:53], v[4:5]
	v_mov_b64_e32 v[50:51], v[2:3]
	v_mov_b64_e32 v[48:49], v[0:1]
	v_mov_b64_e32 v[44:45], v[12:13]
	v_mov_b64_e32 v[42:43], v[10:11]
	v_mov_b64_e32 v[40:41], v[8:9]
	v_mov_b64_e32 v[38:39], v[6:7]
	v_mov_b64_e32 v[36:37], v[4:5]
	v_mov_b64_e32 v[34:35], v[2:3]
	v_mov_b64_e32 v[32:33], v[0:1]
	v_mov_b64_e32 v[28:29], v[12:13]
	v_mov_b64_e32 v[26:27], v[10:11]
	v_mov_b64_e32 v[24:25], v[8:9]
	v_mov_b64_e32 v[22:23], v[6:7]
	v_mov_b64_e32 v[20:21], v[4:5]
	v_mov_b64_e32 v[18:19], v[2:3]
	v_mov_b64_e32 v[16:17], v[0:1]
	s_mul_hi_u32 s1, s9, 0xaaaaaaab
	s_lshr_b32 s1, s1, 1
	s_mul_i32 s1, s1, 0xc000
	v_subrev_u32_e32 v190, s1, v199
	s_mul_hi_u32 s1, s47, 0xaaaaaaab
	s_mul_hi_u32 s0, s46, 0xaaaaaaab
	s_lshr_b32 s12, s1, 1
	s_lshr_b32 s0, s0, 1
	s_mul_i32 s1, s12, 0x6000
	s_mul_i32 s15, s0, 0x6000
	v_subrev_u32_e32 v64, s1, v201
	s_mul_i32 s0, s0, 0xc000
	v_subrev_u32_e32 v219, s15, v183
	v_subrev_u32_e32 v164, s1, v203
	v_subrev_u32_e32 v220, s0, v206
	v_subrev_u32_e32 v221, s0, v207
	v_subrev_u32_e32 v191, s1, v212
	v_subrev_u32_e32 v192, s1, v213
	s_waitcnt lgkmcnt(0)
	s_barrier
.LBB0_90:
	v_add_u32_e32 v141, s14, v184
	v_add_u32_e32 v68, v141, v64
	ds_read_b128 v[64:67], v68
	ds_read_b128 v[68:71], v68 offset:4096
	v_add_u32_e32 v186, v141, v164
	ds_read_b128 v[164:167], v186
	ds_read_b128 v[186:189], v186 offset:4096
	s_waitcnt vmcnt(0)
	v_add_u32_e32 v72, s8, v205
	v_add_u32_e32 v73, v72, v221
	ds_write_b128 v73, v[116:119]
	v_add_u32_e32 v73, v72, v220
	s_add_i32 s13, s14, 0
	ds_write_b128 v73, v[112:115]
	v_add_u32_e32 v73, s13, v219
	ds_write_b128 v73, v[120:123]
	v_exp_f32_e32 v134, v134
	s_waitcnt lgkmcnt(6)
	v_mfma_f32_32x32x16_bf16 v[80:95], v[64:67], v[108:111], v[236:251]
	v_exp_f32_e32 v135, v135
	v_exp_f32_e32 v132, v132
	v_exp_f32_e32 v133, v133
	v_exp_f32_e32 v130, v130
	v_exp_f32_e32 v131, v131
	v_exp_f32_e32 v128, v128
	v_exp_f32_e32 v129, v129
	s_waitcnt lgkmcnt(5)
	v_mfma_f32_32x32x16_bf16 v[64:79], v[68:71], v[108:111], v[236:251]
	v_exp_f32_e32 v126, v126
	v_exp_f32_e32 v127, v127
	v_exp_f32_e32 v124, v124
	v_exp_f32_e32 v125, v125
	s_waitcnt lgkmcnt(4)
	v_mfma_f32_32x32x16_bf16 v[80:95], v[164:167], v[104:107], v[80:95]
	s_waitcnt lgkmcnt(3)
	v_mfma_f32_32x32x16_bf16 v[64:79], v[186:189], v[104:107], v[64:79]
	v_add_u32_e32 v186, v141, v191
	ds_read_b128 v[164:167], v186
	ds_read_b128 v[186:189], v186 offset:4096
	s_waitcnt lgkmcnt(1)
	v_mfma_f32_32x32x16_bf16 v[80:95], v[164:167], v[100:103], v[80:95]
	s_waitcnt lgkmcnt(0)
	v_mfma_f32_32x32x16_bf16 v[64:79], v[186:189], v[100:103], v[64:79]
	v_add_u32_e32 v186, v141, v192
	ds_read_b128 v[164:167], v186
	ds_read_b128 v[186:189], v186 offset:4096
	s_waitcnt lgkmcnt(1)
	v_mfma_f32_32x32x16_bf16 v[80:95], v[164:167], v[96:99], v[80:95]
	v_exp_f32_e32 v166, v136
	v_add_f32_e32 v136, v170, v150
	v_add_f32_e32 v136, v151, v136
	v_add_f32_e32 v136, v171, v136
	v_add_f32_e32 v136, v168, v136
	v_add_f32_e32 v136, v217, v136
	v_add_f32_e32 v136, v169, v136
	v_add_f32_e32 v136, v218, v136
	v_add_f32_e32 v136, v142, v136
	v_add_f32_e32 v136, v146, v136
	v_add_f32_e32 v136, v143, v136
	v_add_f32_e32 v136, v147, v136
	v_exp_f32_e32 v164, v138
	v_add_f32_e32 v136, v144, v136
	v_exp_f32_e32 v165, v139
	v_add_f32_e32 v136, v148, v136
	v_add_f32_e32 v136, v145, v136
	v_exp_f32_e32 v167, v137
	v_add_f32_e32 v136, v149, v136
	v_add_f32_e32 v136, v164, v136
	v_add_f32_e32 v136, v165, v136
	v_add_f32_e32 v136, v166, v136
	v_add_f32_e32 v136, v167, v136
	v_add_f32_e32 v136, v134, v136
	v_add_f32_e32 v136, v135, v136
	v_add_f32_e32 v136, v132, v136
	v_add_f32_e32 v136, v133, v136
	v_add_f32_e32 v136, v130, v136
	v_add_f32_e32 v136, v131, v136
	s_waitcnt lgkmcnt(0)
; #define SBAR() __builtin_amdgcn_sched_barrier(0)
; DEV void finishSM(f32x16& p0, f32x16& p1, float alpha, float& l_reg, bf16x8& pa0, bf16x8& pa1, bf16x8& pa2, bf16x8& pa3) {
; #pragma unroll
;   for (int r = 0; r < 16; ++r) p1[r] = __builtin_amdgcn_exp2f(p1[r]);
;   float ps = 0;
; #pragma unroll
;   for (int r = 0; r < 16; ++r) ps += p0[r];
; #pragma unroll
;   for (int r = 0; r < 16; ++r) ps += p1[r];
;   { auto rr = __builtin_amdgcn_permlane32_swap(__float_as_uint(ps), __float_as_uint(ps), false, false);
;     ps = __uint_as_float(rr[0]) + __uint_as_float(rr[1]); }
;   l_reg = l_reg * alpha + ps;
;     ...
;   PK4(p0, 0, pa0); PK4(p0, 8, pa1); PK4(p1, 0, pa2); PK4(p1, 8, pa3);
;     ...
; }
; template <int D0> DEV void pv_one(f32x16& od, int vb, bf16x8 pa0, bf16x8 pa1, bf16x8 pa2, bf16x8 pa3) {
;   const s16x4 l0 = tr_read<v_rd_off(D0, 0, 0)>(vb), h0 = tr_read<v_rd_off(D0, 0, 1)>(vb), l1 = tr_read<v_rd_off(D0, 1, 0)>(vb), h1 = tr_read<v_rd_off(D0, 1, 1)>(vb);
;   const s16x4 l2 = tr_read<v_rd_off(D0, 2, 0)>(vb), h2 = tr_read<v_rd_off(D0, 2, 1)>(vb), l3 = tr_read<v_rd_off(D0, 3, 0)>(vb), h3 = tr_read<v_rd_off(D0, 3, 1)>(vb);
;   asm volatile("s_waitcnt lgkmcnt(0)" ::: "memory"); SBAR();
;     ...
;   od = __builtin_amdgcn_mfma_f32_32x32x16_bf16(pa0, PK(l0, h0), od, 0, 0, 0);
;   od = __builtin_amdgcn_mfma_f32_32x32x16_bf16(pa1, PK(l1, h1), od, 0, 0, 0);
;   od = __builtin_amdgcn_mfma_f32_32x32x16_bf16(pa2, PK(l2, h2), od, 0, 0, 0);
;   od = __builtin_amdgcn_mfma_f32_32x32x16_bf16(pa3, PK(l3, h3), od, 0, 0, 0);
;     ...
; }
; DEV void pv_d0(f32x16* o, int vb, bf16x8 pa0, bf16x8 pa1, bf16x8 pa2, bf16x8 pa3) {
;   pv_one<0>(o[0], vb, pa0, pa1, pa2, pa3); pv_one<1>(o[1], vb, pa0, pa1, pa2, pa3); pv_one<2>(o[2], vb, pa0, pa1, pa2, pa3); pv_one<3>(o[3], vb, pa0, pa1, pa2, pa3);
; }
	v_mfma_f32_32x32x16_bf16 v[64:79], v[186:189], v[96:99], v[64:79]
	v_add_f32_e32 v136, v128, v136
	v_add_f32_e32 v136, v129, v136
	v_add_f32_e32 v136, v126, v136
	v_add_f32_e32 v136, v127, v136
	v_add_f32_e32 v136, v124, v136
	v_add_f32_e32 v214, v125, v136
	v_mov_b32_e32 v215, v214
	v_cvt_pk_bf16_f32 v136, v150, v170
	v_cvt_pk_bf16_f32 v138, v168, v217
	s_nop 1
	v_permlane32_swap_b32_e32 v214, v215
	v_cvt_pk_bf16_f32 v137, v151, v171
	v_cvt_pk_bf16_f32 v139, v169, v218
	v_permlane32_swap_b32_e32 v136, v138
	v_cvt_pk_bf16_f32 v142, v142, v146
	v_cvt_pk_bf16_f32 v143, v143, v147
	v_cvt_pk_bf16_f32 v144, v144, v148
	v_cvt_pk_bf16_f32 v145, v145, v149
	v_cvt_pk_bf16_f32 v146, v164, v165
	v_cvt_pk_bf16_f32 v147, v166, v167
	v_cvt_pk_bf16_f32 v148, v134, v135
	v_cvt_pk_bf16_f32 v149, v132, v133
	v_cvt_pk_bf16_f32 v164, v130, v131
	v_cvt_pk_bf16_f32 v165, v128, v129
	v_cvt_pk_bf16_f32 v166, v126, v127
	v_cvt_pk_bf16_f32 v167, v124, v125
	v_permlane32_swap_b32_e32 v137, v139
	v_permlane32_swap_b32_e32 v142, v144
	v_permlane32_swap_b32_e32 v143, v145
	v_permlane32_swap_b32_e32 v146, v148
	v_permlane32_swap_b32_e32 v147, v149
	v_permlane32_swap_b32_e32 v164, v166
	v_permlane32_swap_b32_e32 v165, v167
	v_lshl_add_u64 v[168:169], v[160:161], 0, s[82:83]
	v_add_co_u32_e32 v124, vcc, s94, v168
	v_lshl_add_u64 v[170:171], v[158:159], 0, s[82:83]
	s_nop 0
	v_addc_co_u32_e32 v125, vcc, 0, v169, vcc
	v_add_co_u32_e32 v128, vcc, s95, v168
	s_mov_b32 s0, 0x1868e000
	s_nop 0
	v_addc_co_u32_e32 v129, vcc, 0, v169, vcc
	v_add_co_u32_e32 v132, vcc, s0, v170
	global_load_dwordx4 v[124:127], v[124:125], off
	s_nop 0
	global_load_dwordx4 v[128:131], v[128:129], off
	v_addc_co_u32_e32 v133, vcc, 0, v171, vcc
	global_load_dwordx4 v[132:135], v[132:133], off
	v_add_u32_e32 v150, s8, v190
	ds_read_b64_tr_b16 v[186:187], v150 offset:0
	ds_read_b64_tr_b16 v[188:189], v150 offset:0x800
	ds_read_b64_tr_b16 v[190:191], v150 offset:0x1000
	ds_read_b64_tr_b16 v[192:193], v150 offset:0x1800
	ds_read_b64_tr_b16 v[222:223], v150 offset:0x2000
	ds_read_b64_tr_b16 v[224:225], v150 offset:0x2800
	ds_read_b64_tr_b16 v[226:227], v150 offset:0x3000
	ds_read_b64_tr_b16 v[228:229], v150 offset:0x3800
	s_waitcnt lgkmcnt(0)
	s_nop 0
	v_mfma_f32_32x32x16_bf16 v[0:15], v[136:139], v[186:189], v[0:15]
	ds_read_b64_tr_b16 v[186:187], v150 offset:0x200
	ds_read_b64_tr_b16 v[188:189], v150 offset:0xa00
	v_mfma_f32_32x32x16_bf16 v[0:15], v[142:145], v[190:193], v[0:15]
	ds_read_b64_tr_b16 v[190:191], v150 offset:0x1200
	ds_read_b64_tr_b16 v[192:193], v150 offset:0x1a00
	v_mfma_f32_32x32x16_bf16 v[0:15], v[146:149], v[222:225], v[0:15]
	ds_read_b64_tr_b16 v[222:223], v150 offset:0x2200
	ds_read_b64_tr_b16 v[224:225], v150 offset:0x2a00
	v_mfma_f32_32x32x16_bf16 v[0:15], v[164:167], v[226:229], v[0:15]
	ds_read_b64_tr_b16 v[226:227], v150 offset:0x3200
	ds_read_b64_tr_b16 v[228:229], v150 offset:0x3a00
	s_waitcnt lgkmcnt(0)
	v_mfma_f32_32x32x16_bf16 v[48:63], v[136:139], v[186:189], v[48:63]
	ds_read_b64_tr_b16 v[186:187], v150 offset:0x400
	ds_read_b64_tr_b16 v[188:189], v150 offset:0xc00
	v_mfma_f32_32x32x16_bf16 v[48:63], v[142:145], v[190:193], v[48:63]
	ds_read_b64_tr_b16 v[190:191], v150 offset:0x1400
	ds_read_b64_tr_b16 v[192:193], v150 offset:0x1c00
	v_mfma_f32_32x32x16_bf16 v[48:63], v[146:149], v[222:225], v[48:63]
	ds_read_b64_tr_b16 v[222:223], v150 offset:0x2400
	ds_read_b64_tr_b16 v[224:225], v150 offset:0x2c00
	v_mfma_f32_32x32x16_bf16 v[48:63], v[164:167], v[226:229], v[48:63]
	ds_read_b64_tr_b16 v[226:227], v150 offset:0x3400
	ds_read_b64_tr_b16 v[228:229], v150 offset:0x3c00
	s_waitcnt lgkmcnt(0)
	v_mfma_f32_32x32x16_bf16 v[32:47], v[136:139], v[186:189], v[32:47]
	ds_read_b64_tr_b16 v[186:187], v150 offset:0x600
	ds_read_b64_tr_b16 v[188:189], v150 offset:0xe00
	v_mfma_f32_32x32x16_bf16 v[32:47], v[142:145], v[190:193], v[32:47]
	ds_read_b64_tr_b16 v[190:191], v150 offset:0x1600
	ds_read_b64_tr_b16 v[192:193], v150 offset:0x1e00
	v_mfma_f32_32x32x16_bf16 v[32:47], v[146:149], v[222:225], v[32:47]
	ds_read_b64_tr_b16 v[222:223], v150 offset:0x2600
	ds_read_b64_tr_b16 v[224:225], v150 offset:0x2e00
	v_mfma_f32_32x32x16_bf16 v[32:47], v[164:167], v[226:229], v[32:47]
	ds_read_b64_tr_b16 v[226:227], v150 offset:0x3600
	ds_read_b64_tr_b16 v[228:229], v150 offset:0x3e00
	s_waitcnt lgkmcnt(0)
	v_mfma_f32_32x32x16_bf16 v[16:31], v[136:139], v[186:189], v[16:31]
	v_max_f32_e32 v136, v80, v81
	v_max3_f32 v137, v64, v65, v66
	v_max3_f32 v136, v136, v82, v83
	v_max3_f32 v137, v137, v67, v68
	v_max3_f32 v136, v136, v84, v85
	v_max3_f32 v137, v137, v69, v70
	v_max3_f32 v136, v136, v86, v87
	v_max3_f32 v137, v137, v71, v72
	v_mfma_f32_32x32x16_bf16 v[16:31], v[142:145], v[190:193], v[16:31]
	v_max3_f32 v136, v136, v88, v89
	v_max3_f32 v137, v137, v73, v74
	v_max3_f32 v136, v136, v90, v91
	v_max3_f32 v137, v137, v75, v76
	v_max3_f32 v136, v136, v92, v93
	v_max3_f32 v137, v137, v77, v78
	v_max3_f32 v136, v136, v94, v95
	v_max3_f32 v136, v136, v137, v79
	v_mfma_f32_32x32x16_bf16 v[16:31], v[146:149], v[222:225], v[16:31]
	v_mov_b32_e32 v137, v136
	s_nop 1
	v_permlane32_swap_b32_e32 v136, v137
	v_max_f32_e32 v136, v136, v137
	v_cmp_ge_f32_e32 vcc, s18, v136
	v_mfma_f32_32x32x16_bf16 v[16:31], v[164:167], v[226:229], v[16:31]
	s_cmp_eq_u64 vcc, exec
	s_cselect_b64 s[0:1], -1, 0
	s_cbranch_scc1 .Lattn_fast3
	v_max_f32_e32 v136, 0, v136
	v_exp_f32_e64 v137, -v136

; #define SBAR() __builtin_amdgcn_sched_barrier(0)
; #define SLOAD(i, k0) do { sr_[i].vs0 = *reinterpret_cast<const bf16x8*>(&Vh[(size_t)((k0) + sr) * 128 + sc]); sr_[i].vs1 = *reinterpret_cast<const bf16x8*>(&Vh[(size_t)((k0) + 32 + sr) * 128 + sc]); \
;     sr_[i].ks0 = *reinterpret_cast<const bf16x8*>(&Kh[(size_t)((k0) + kr) * 64 + kc]); } while (0)
; #define SWRITE(b, i) do { *(bf16x8*)(V_lds + (b) * AT_SHM_V + vst0) = sr_[i].vs0; *(bf16x8*)(V_lds + (b) * AT_SHM_V + vst1) = sr_[i].vs1; \
;     *(bf16x8*)(K_lds + (b) * AT_SHM_K + kst) = sr_[i].ks0; } while (0)
; #define SWAIT() asm volatile("s_waitcnt vmcnt(3)" ::: "memory")
; #define RESC(a) do { if (__any((a) < 1.f)) { if (hi == 0) al_l[r32] = (a); asm volatile("s_waitcnt lgkmcnt(0)" ::: "memory"); \
;     for (int d = 0; d < 4; ++d) for (int r = 0; r < 16; ++r) o[d][r] *= al_l[crow(r, hi)]; } } while (0)
; DEV void attn_pass(const u16* __restrict__ Qb, const u16* __restrict__ Kh, const u16* __restrict__ Vh, int seq, f32x16* o, float* rli) {
;     ...
;   for (int j = 1; j + 1 < NT; j += 2) {
;     const int bm1 = (j - 1) % 3, b0 = j % 3, b1 = (j + 1) % 3, b2 = (j + 2) % 3;
;     SBAR(); qkt(pB0, pB1, K_lds + b0 * AT_SHM_K, qr, r32, hi);
;     finishSM(pA0, pA1, alA, l_reg, pa0, pa1, pa2, pa3); SBAR();
;     SLOAD(SO, (j + 2) * 64); SBAR();
;     pv_d0(o, vb0 + bm1 * AT_SHM_V, pa0, pa1, pa2, pa3); partialSM(pB0, pB1, m_reg, mnB, alB);
;     SWAIT(); SWRITE(b1, SE);
;     RESC(alB); __syncthreads();
;     SBAR(); qkt(pA0, pA1, K_lds + b1 * AT_SHM_K, qr, r32, hi);
;     finishSM(pB0, pB1, alB, l_reg, pa0, pa1, pa2, pa3); SBAR();
;     if (j + 3 < NT) SLOAD(SE, (j + 3) * 64); SBAR();
;     pv_d0(o, vb0 + b0 * AT_SHM_V, pa0, pa1, pa2, pa3); partialSM(pA0, pA1, m_reg, mnA, alA);
;     SWAIT(); SWRITE(b2, SO);
;     RESC(alA); __syncthreads();
;   }
.LBB0_100:
	v_exp_f32_e32 v150, v80
	v_exp_f32_e32 v170, v81
	v_exp_f32_e32 v151, v82
	v_exp_f32_e32 v171, v83
	v_exp_f32_e32 v168, v84
	v_exp_f32_e32 v217, v85
	v_exp_f32_e32 v169, v86
	v_exp_f32_e32 v218, v87
	v_exp_f32_e32 v142, v88
	v_exp_f32_e32 v146, v89
	v_exp_f32_e32 v143, v90
	v_exp_f32_e32 v147, v91
	v_exp_f32_e32 v144, v92
	v_exp_f32_e32 v148, v93
	v_exp_f32_e32 v145, v94
	v_exp_f32_e32 v149, v95
	v_mov_b64_e32 v[138:139], v[64:65]
	v_add_f32_e32 v64, v214, v215
	s_mov_b64 s[0:1], 0x4000
	v_fmac_f32_e32 v64, v185, v174
	v_add_f32_e32 v174, v219, v220
	v_lshl_add_u64 v[158:159], v[158:159], 0, s[0:1]
	s_mov_b64 s[0:1], 0x8000
	v_mov_b64_e32 v[136:137], v[66:67]
	v_mov_b64_e32 v[134:135], v[68:69]
	v_mov_b64_e32 v[132:133], v[70:71]
	v_mov_b64_e32 v[130:131], v[72:73]
	v_mov_b64_e32 v[128:129], v[74:75]
	v_mov_b64_e32 v[126:127], v[76:77]
	v_mov_b64_e32 v[124:125], v[78:79]
	v_fmac_f32_e32 v174, v64, v216
	s_addk_i32 s14, 0x4000
	s_add_i32 s46, s46, 2
	s_add_i32 s48, s48, 2
	s_add_i32 s9, s9, 2
	s_add_i32 s8, s8, 0x8000
	v_lshl_add_u64 v[160:161], v[160:161], 0, s[0:1]
	s_add_i32 s64, s64, 2
	s_add_i32 s47, s47, 2
	s_mul_hi_u32 s1, s9, 0xaaaaaaab
	s_lshr_b32 s1, s1, 1
	s_mul_i32 s1, s1, 0xc000
	v_subrev_u32_e32 v190, s1, v199
	s_mul_hi_u32 s1, s47, 0xaaaaaaab
	s_mul_hi_u32 s0, s46, 0xaaaaaaab
	s_lshr_b32 s12, s1, 1
	s_lshr_b32 s0, s0, 1
	s_mul_i32 s1, s12, 0x6000
	s_mul_i32 s15, s0, 0x6000
	v_subrev_u32_e32 v64, s1, v201
	s_mul_i32 s0, s0, 0xc000
	v_subrev_u32_e32 v219, s15, v183
	v_subrev_u32_e32 v164, s1, v203
	v_subrev_u32_e32 v220, s0, v206
	v_subrev_u32_e32 v221, s0, v207
	v_subrev_u32_e32 v191, s1, v212
	v_subrev_u32_e32 v192, s1, v213
	s_and_b64 vcc, exec, s[10:11]
	s_waitcnt lgkmcnt(0)
	s_barrier
	s_cbranch_vccnz .LBB0_102
	v_mov_b32_e32 v185, v141
	s_branch .LBB0_90
